# v52 plus non-temporal hint on the log-forget f32 stores and the up-proj gate-output stores
# baseline (speedup 1.0000x reference)
.LBB0_858:
	v_add_u32_e32 v112, 0xfffffe00, v170
	v_ashrrev_i32_e32 v113, 31, v112
	v_lshlrev_b64 v[130:131], 2, v[112:113]
	v_lshl_add_u64 v[112:113], s[48:49], 0, v[130:131]
	global_load_dwordx4 v[116:119], v[112:113], off
	s_nop 0
	global_load_dwordx4 v[112:115], v[112:113], off offset:16
	v_mul_f32_e64 v132, |v140|, s20
	v_mul_f32_e64 v133, |v136|, s20
	v_exp_f32_e32 v132, v132
	v_mul_f32_e64 v134, |v141|, s20
	v_exp_f32_e32 v133, v133
	v_mul_f32_e64 v135, |v137|, s20
	v_exp_f32_e32 v134, v134
	v_mul_f32_e64 v144, |v142|, s20
	v_exp_f32_e32 v135, v135
	v_cmp_nle_f32_e32 vcc, 0, v140
	v_exp_f32_e32 v144, v144
	v_mul_f32_e64 v147, |v139|, s20
	v_cndmask_b32_e32 v140, 1.0, v132, vcc
	v_cmp_nle_f32_e32 vcc, 0, v136
	v_exp_f32_e32 v148, v147
	v_add_f32_e32 v132, 1.0, v132
	v_cndmask_b32_e32 v136, 1.0, v133, vcc
	v_cmp_nle_f32_e32 vcc, 0, v141
	v_add_f32_e32 v133, 1.0, v133
	v_rcp_f32_e32 v132, v132
	v_cndmask_b32_e32 v141, 1.0, v134, vcc
	v_cmp_nle_f32_e32 vcc, 0, v137
	v_add_f32_e32 v134, 1.0, v134
	v_rcp_f32_e32 v134, v134
	v_cndmask_b32_e32 v137, 1.0, v135, vcc
	v_cmp_nle_f32_e32 vcc, 0, v142
	v_rcp_f32_e32 v133, v133
	v_mul_f32_e64 v145, |v138|, s20
	v_cndmask_b32_e32 v142, 1.0, v144, vcc
	v_add_f32_e32 v144, 1.0, v144
	v_rcp_f32_e32 v144, v144
	v_add_f32_e32 v147, 1.0, v148
	v_exp_f32_e32 v145, v145
	v_rcp_f32_e32 v149, v147
	v_mul_f32_e32 v132, v140, v132
	v_mul_f32_e32 v147, v141, v134
	v_mul_f32_e64 v146, |v143|, s20
	v_mul_f32_e32 v133, v136, v133
	v_mul_f32_e32 v142, v142, v144
	v_exp_f32_e32 v146, v146
	v_cmp_nle_f32_e32 vcc, 0, v138
	v_add_f32_e32 v135, 1.0, v135
	v_rcp_f32_e32 v135, v135
	v_cndmask_b32_e32 v138, 1.0, v145, vcc
	v_add_f32_e32 v145, 1.0, v145
	v_cmp_nle_f32_e32 vcc, 0, v143
	v_rcp_f32_e32 v145, v145
	v_mul_f32_e32 v150, v137, v135
	v_cndmask_b32_e32 v143, 1.0, v146, vcc
	v_cmp_nle_f32_e32 vcc, 0, v139
	v_add_f32_e32 v146, 1.0, v146
	v_rcp_f32_e32 v146, v146
	v_mul_f32_e32 v144, v138, v145
	s_mov_b64 s[4:5], 0x40000
	v_mul_f32_e32 v143, v143, v146
	s_waitcnt vmcnt(1)
	v_sub_f32_e32 v141, 1.0, v116
	v_sub_f32_e32 v136, 1.0, v118
	v_fma_f32 v132, v132, v141, v116
	v_fma_f32 v142, v142, v136, v118
	v_log_f32_e32 v132, v132
	v_log_f32_e32 v142, v142
	s_waitcnt vmcnt(0)
	v_sub_f32_e32 v139, 1.0, v115
	v_sub_f32_e32 v135, 1.0, v114
	v_mul_f32_e32 v132, 0x3f317218, v132
	v_mul_f32_e32 v151, 0x3f317218, v142
	v_max_f32_e32 v142, 0xc2700000, v132
	v_cndmask_b32_e32 v132, 1.0, v148, vcc
	v_mul_f32_e32 v132, v132, v149
	v_fma_f32 v132, v132, v139, v115
	v_fma_f32 v144, v144, v135, v114
	v_log_f32_e32 v132, v132
	v_log_f32_e32 v144, v144
	v_sub_f32_e32 v140, 1.0, v112
	v_sub_f32_e32 v138, 1.0, v117
	v_sub_f32_e32 v137, 1.0, v113
	v_sub_f32_e32 v134, 1.0, v119
	v_fma_f32 v133, v133, v140, v112
	v_fma_f32 v145, v147, v138, v117
	v_fma_f32 v146, v150, v137, v113
	v_fma_f32 v143, v143, v134, v119
	v_log_f32_e32 v133, v133
	v_mul_f32_e32 v132, 0x3f317218, v132
	v_log_f32_e32 v145, v145
	v_log_f32_e32 v146, v146
	v_log_f32_e32 v150, v143
	v_mul_f32_e32 v152, 0x3f317218, v144
	v_max_f32_e32 v149, 0xc2700000, v132
	v_mul_f32_e64 v132, |v120|, s20
	v_max_f32_e32 v148, 0xc2700000, v152
	v_exp_f32_e32 v152, v132
	v_mul_f32_e32 v133, 0x3f317218, v133
	v_mul_f32_e32 v143, 0x3f317218, v145
	v_mul_f32_e32 v145, 0x3f317218, v146
	v_max_f32_e32 v146, 0xc2700000, v133
	v_mul_f32_e32 v133, 0x3f317218, v150
	v_max_f32_e32 v147, 0xc2700000, v145
	v_max_f32_e32 v145, 0xc2700000, v133
	v_lshlrev_b64 v[132:133], 11, v[128:129]
	v_add_f32_e32 v129, 1.0, v152
	v_rcp_f32_e32 v129, v129
	v_cmp_nle_f32_e32 vcc, 0, v120
	v_lshl_add_u64 v[132:133], s[6:7], 0, v[132:133]
	v_max_f32_e32 v143, 0xc2700000, v143
	v_cndmask_b32_e32 v120, 1.0, v152, vcc
	v_mul_f32_e32 v120, v120, v129
	v_mul_f32_e64 v129, |v124|, s20
	v_exp_f32_e32 v129, v129
	v_max_f32_e32 v144, 0xc2700000, v151
	v_lshl_add_u64 v[150:151], v[132:133], 0, v[130:131]
	global_store_dwordx4 v[150:151], v[142:145], off nt
	v_fma_f32 v120, v120, v141, v116
	v_cmp_nle_f32_e32 vcc, 0, v124
	v_add_f32_e32 v142, 1.0, v129
	v_rcp_f32_e32 v142, v142
	v_log_f32_e32 v120, v120
	v_cndmask_b32_e32 v124, 1.0, v129, vcc
	v_mul_f32_e64 v129, |v121|, s20
	v_exp_f32_e32 v129, v129
	v_mul_f32_e32 v124, v124, v142
	v_mul_f32_e32 v120, 0x3f317218, v120
	v_fma_f32 v124, v124, v140, v112
	v_log_f32_e32 v142, v124
	v_max_f32_e32 v124, 0xc2700000, v120
	v_add_f32_e32 v120, 1.0, v129
	v_rcp_f32_e32 v120, v120
	v_cmp_nle_f32_e32 vcc, 0, v121
	global_store_dwordx4 v[150:151], v[146:149], off offset:16 nt
	v_mul_f32_e32 v142, 0x3f317218, v142
	v_cndmask_b32_e32 v121, 1.0, v129, vcc
	v_mul_f32_e32 v120, v121, v120
	v_mul_f32_e64 v121, |v125|, s20
	v_exp_f32_e32 v121, v121
	v_cmp_nle_f32_e32 vcc, 0, v125
	v_fma_f32 v120, v120, v138, v117
	v_log_f32_e32 v120, v120
	v_add_f32_e32 v129, 1.0, v121
	v_rcp_f32_e32 v129, v129
	v_cndmask_b32_e32 v121, 1.0, v121, vcc
	v_mul_f32_e64 v125, |v122|, s20
	v_mul_f32_e32 v120, 0x3f317218, v120
	v_mul_f32_e32 v121, v121, v129
	v_fma_f32 v121, v121, v137, v113
	v_log_f32_e32 v121, v121
	v_exp_f32_e32 v129, v125
	v_max_f32_e32 v125, 0xc2700000, v120
	v_cmp_nle_f32_e32 vcc, 0, v122
	v_mul_f32_e32 v120, 0x3f317218, v121
	v_max_f32_e32 v143, 0xc2700000, v120
	v_add_f32_e32 v120, 1.0, v129
	v_mul_f32_e64 v121, |v126|, s20
	v_rcp_f32_e32 v120, v120
	v_exp_f32_e32 v121, v121
	v_cndmask_b32_e32 v122, 1.0, v129, vcc
	v_cmp_nle_f32_e32 vcc, 0, v126
	v_mul_f32_e32 v120, v122, v120
	v_add_f32_e32 v122, 1.0, v121
	v_rcp_f32_e32 v122, v122
	v_cndmask_b32_e32 v121, 1.0, v121, vcc
	v_fma_f32 v120, v120, v136, v118
	v_log_f32_e32 v120, v120
	v_mul_f32_e32 v121, v121, v122
	v_fma_f32 v121, v121, v135, v114
	v_mul_f32_e64 v122, |v123|, s20
	v_log_f32_e32 v121, v121
	v_exp_f32_e32 v122, v122
	v_mul_f32_e32 v120, 0x3f317218, v120
	v_max_f32_e32 v126, 0xc2700000, v120
	v_mul_f32_e32 v120, 0x3f317218, v121
	v_add_f32_e32 v121, 1.0, v122
	v_mul_f32_e64 v129, |v127|, s20
	v_rcp_f32_e32 v121, v121
	v_exp_f32_e32 v129, v129
	v_cmp_nle_f32_e32 vcc, 0, v123
	v_max_f32_e32 v144, 0xc2700000, v120
	v_max_f32_e32 v142, 0xc2700000, v142
	v_cndmask_b32_e32 v122, 1.0, v122, vcc
	v_mul_f32_e32 v121, v122, v121
	v_add_f32_e32 v122, 1.0, v129
	v_rcp_f32_e32 v122, v122
	v_cmp_nle_f32_e32 vcc, 0, v127
	v_fma_f32 v121, v121, v134, v119
	v_log_f32_e32 v121, v121
	v_cndmask_b32_e32 v123, 1.0, v129, vcc
	v_mul_f32_e32 v122, v123, v122
	v_fma_f32 v122, v122, v139, v115
	v_log_f32_e32 v122, v122
	v_mul_f32_e32 v120, 0x3f317218, v121
	v_max_f32_e32 v127, 0xc2700000, v120
	v_cmp_nle_f32_e32 vcc, 0, v104
	v_mul_f32_e32 v120, 0x3f317218, v122
	v_max_f32_e32 v145, 0xc2700000, v120
	v_or_b32_e32 v120, 16, v128
	v_ashrrev_i32_e32 v121, 31, v120
	v_lshlrev_b64 v[120:121], 11, v[120:121]
	v_mul_f32_e64 v122, |v104|, s20
	v_lshl_add_u64 v[120:121], s[6:7], 0, v[120:121]
	v_exp_f32_e32 v129, v122
	v_lshl_add_u64 v[122:123], v[120:121], 0, v[130:131]
	global_store_dwordx4 v[122:123], v[124:127], off nt
	global_store_dwordx4 v[122:123], v[142:145], off offset:16 nt
	v_add_f32_e32 v146, 1.0, v129
	v_mul_f32_e64 v124, |v108|, s20
	v_exp_f32_e32 v124, v124
	v_rcp_f32_e32 v146, v146
	v_cndmask_b32_e32 v104, 1.0, v129, vcc
	v_cmp_nle_f32_e32 vcc, 0, v108
	v_add_f32_e32 v122, 1.0, v124
	v_rcp_f32_e32 v122, v122
	v_mul_f32_e32 v104, v104, v146
	v_fma_f32 v104, v104, v141, v116
	v_cndmask_b32_e32 v108, 1.0, v124, vcc
	v_log_f32_e32 v104, v104
	v_mul_f32_e32 v108, v108, v122
	v_mul_f32_e64 v122, |v105|, s20
	v_exp_f32_e32 v122, v122
	v_mul_f32_e32 v104, 0x3f317218, v104
	v_fma_f32 v108, v108, v140, v112
	v_log_f32_e32 v123, v108
	v_max_f32_e32 v108, 0xc2700000, v104
	v_add_f32_e32 v104, 1.0, v122
	v_rcp_f32_e32 v104, v104
	v_cmp_nle_f32_e32 vcc, 0, v105
	v_mul_f32_e32 v123, 0x3f317218, v123
	s_nop 0
	v_cndmask_b32_e32 v105, 1.0, v122, vcc
	v_mul_f32_e32 v104, v105, v104
	v_mul_f32_e64 v105, |v109|, s20
	v_exp_f32_e32 v105, v105
	v_max_f32_e32 v122, 0xc2700000, v123
	v_cmp_nle_f32_e32 vcc, 0, v109
	v_fma_f32 v104, v104, v138, v117
	v_add_f32_e32 v123, 1.0, v105
	v_rcp_f32_e32 v123, v123
	v_cndmask_b32_e32 v105, 1.0, v105, vcc
	v_log_f32_e32 v104, v104
	v_mul_f32_e64 v109, |v106|, s20
	v_mul_f32_e32 v105, v105, v123
	v_fma_f32 v105, v105, v137, v113
	v_log_f32_e32 v105, v105
	v_exp_f32_e32 v124, v109
	v_mul_f32_e32 v104, 0x3f317218, v104
	v_max_f32_e32 v109, 0xc2700000, v104
	v_mul_f32_e32 v104, 0x3f317218, v105
	v_max_f32_e32 v123, 0xc2700000, v104
	v_add_f32_e32 v104, 1.0, v124
	v_mul_f32_e64 v105, |v110|, s20
	v_rcp_f32_e32 v104, v104
	v_exp_f32_e32 v105, v105
	v_cmp_nle_f32_e32 vcc, 0, v106
	s_nop 1
	v_cndmask_b32_e32 v106, 1.0, v124, vcc
	v_mul_f32_e32 v104, v106, v104
	v_add_f32_e32 v106, 1.0, v105
	v_rcp_f32_e32 v106, v106
	v_cmp_nle_f32_e32 vcc, 0, v110
	v_fma_f32 v104, v104, v136, v118
	v_log_f32_e32 v104, v104
	v_cndmask_b32_e32 v105, 1.0, v105, vcc
	v_mul_f32_e32 v105, v105, v106
	v_fma_f32 v105, v105, v135, v114
	v_mul_f32_e64 v106, |v107|, s20
	v_log_f32_e32 v105, v105
	v_exp_f32_e32 v106, v106
	v_mul_f32_e32 v104, 0x3f317218, v104
	v_max_f32_e32 v110, 0xc2700000, v104
	v_mul_f32_e32 v104, 0x3f317218, v105
	v_add_f32_e32 v105, 1.0, v106
	v_mul_f32_e64 v124, |v111|, s20
	v_rcp_f32_e32 v105, v105
	v_exp_f32_e32 v124, v124
	v_cmp_nle_f32_e32 vcc, 0, v107
	s_nop 1
	v_cndmask_b32_e32 v106, 1.0, v106, vcc
	v_mul_f32_e32 v105, v106, v105
	v_add_f32_e32 v106, 1.0, v124
	v_rcp_f32_e32 v106, v106
	v_cmp_nle_f32_e32 vcc, 0, v111
	v_fma_f32 v105, v105, v134, v119
	v_log_f32_e32 v105, v105
	v_cndmask_b32_e32 v107, 1.0, v124, vcc
	v_mul_f32_e32 v106, v107, v106
	v_fma_f32 v106, v106, v139, v115
	v_log_f32_e32 v106, v106
	v_max_f32_e32 v124, 0xc2700000, v104
	v_mul_f32_e32 v104, 0x3f317218, v105
	v_max_f32_e32 v111, 0xc2700000, v104
	v_mul_f32_e32 v104, 0x3f317218, v106
	v_max_f32_e32 v125, 0xc2700000, v104
	v_or_b32_e32 v104, 32, v128
	v_ashrrev_i32_e32 v105, 31, v104
	v_lshlrev_b64 v[104:105], 11, v[104:105]
	v_mul_f32_e64 v106, |v96|, s20
	v_lshl_add_u64 v[104:105], s[6:7], 0, v[104:105]
	v_exp_f32_e32 v126, v106
	v_lshl_add_u64 v[106:107], v[104:105], 0, v[130:131]
	global_store_dwordx4 v[106:107], v[108:111], off nt
	global_store_dwordx4 v[106:107], v[122:125], off offset:16 nt
	v_add_f32_e32 v127, 1.0, v126
	v_mul_f32_e64 v108, |v100|, s20
	v_exp_f32_e32 v108, v108
	v_rcp_f32_e32 v127, v127
	v_cmp_nle_f32_e32 vcc, 0, v96
	v_add_f32_e32 v106, 1.0, v108
	v_rcp_f32_e32 v106, v106
	v_cndmask_b32_e32 v96, 1.0, v126, vcc
	v_mul_f32_e32 v96, v96, v127
	v_cmp_nle_f32_e32 vcc, 0, v100
	v_fma_f32 v96, v96, v141, v116
	v_log_f32_e32 v96, v96
	v_cndmask_b32_e32 v100, 1.0, v108, vcc
	v_mul_f32_e32 v100, v100, v106
	v_mul_f32_e64 v106, |v97|, s20
	v_exp_f32_e32 v106, v106
	v_mul_f32_e32 v96, 0x3f317218, v96
	v_fma_f32 v100, v100, v140, v112
	v_log_f32_e32 v107, v100
	v_max_f32_e32 v100, 0xc2700000, v96
	v_add_f32_e32 v96, 1.0, v106
	v_rcp_f32_e32 v96, v96
	v_cmp_nle_f32_e32 vcc, 0, v97
	v_mul_f32_e32 v107, 0x3f317218, v107
	s_nop 0
	v_cndmask_b32_e32 v97, 1.0, v106, vcc
	v_mul_f32_e32 v96, v97, v96
	v_mul_f32_e64 v97, |v101|, s20
	v_exp_f32_e32 v97, v97
	v_max_f32_e32 v106, 0xc2700000, v107
	v_cmp_nle_f32_e32 vcc, 0, v101
	v_fma_f32 v96, v96, v138, v117
	v_add_f32_e32 v107, 1.0, v97
	v_rcp_f32_e32 v107, v107
	v_cndmask_b32_e32 v97, 1.0, v97, vcc
	v_log_f32_e32 v96, v96
	v_mul_f32_e64 v101, |v98|, s20
	v_mul_f32_e32 v97, v97, v107
	v_fma_f32 v97, v97, v137, v113
	v_log_f32_e32 v97, v97
	v_exp_f32_e32 v108, v101
	v_mul_f32_e32 v96, 0x3f317218, v96
	v_max_f32_e32 v101, 0xc2700000, v96
	v_mul_f32_e32 v96, 0x3f317218, v97
	v_max_f32_e32 v107, 0xc2700000, v96
	v_add_f32_e32 v96, 1.0, v108
	v_mul_f32_e64 v97, |v102|, s20
	v_rcp_f32_e32 v96, v96
	v_exp_f32_e32 v97, v97
	v_cmp_nle_f32_e32 vcc, 0, v98
	s_nop 1
	v_cndmask_b32_e32 v98, 1.0, v108, vcc
	v_mul_f32_e32 v96, v98, v96
	v_add_f32_e32 v98, 1.0, v97
	v_rcp_f32_e32 v98, v98
	v_cmp_nle_f32_e32 vcc, 0, v102
	v_fma_f32 v96, v96, v136, v118
	v_log_f32_e32 v96, v96
	v_cndmask_b32_e32 v97, 1.0, v97, vcc
	v_mul_f32_e32 v97, v97, v98
	v_fma_f32 v97, v97, v135, v114
	v_mul_f32_e64 v98, |v99|, s20
	v_log_f32_e32 v97, v97
	v_exp_f32_e32 v98, v98
	v_mul_f32_e32 v96, 0x3f317218, v96
	v_max_f32_e32 v102, 0xc2700000, v96
	v_mul_f32_e32 v96, 0x3f317218, v97
	v_add_f32_e32 v97, 1.0, v98
	v_mul_f32_e64 v108, |v103|, s20
	v_rcp_f32_e32 v97, v97
	v_exp_f32_e32 v108, v108
	v_cmp_nle_f32_e32 vcc, 0, v99
	s_nop 1
	v_cndmask_b32_e32 v98, 1.0, v98, vcc
	v_mul_f32_e32 v97, v98, v97
	v_add_f32_e32 v98, 1.0, v108
	v_rcp_f32_e32 v98, v98
	v_cmp_nle_f32_e32 vcc, 0, v103
	v_fma_f32 v97, v97, v134, v119
	v_log_f32_e32 v97, v97
	v_cndmask_b32_e32 v99, 1.0, v108, vcc
	v_mul_f32_e32 v98, v99, v98
	v_fma_f32 v98, v98, v139, v115
	v_log_f32_e32 v98, v98
	v_max_f32_e32 v108, 0xc2700000, v96
	v_mul_f32_e32 v96, 0x3f317218, v97
	v_max_f32_e32 v103, 0xc2700000, v96
	v_mul_f32_e32 v96, 0x3f317218, v98
	v_max_f32_e32 v109, 0xc2700000, v96
	v_or_b32_e32 v96, 48, v128
	v_ashrrev_i32_e32 v97, 31, v96
	v_lshlrev_b64 v[96:97], 11, v[96:97]
	v_mul_f32_e64 v98, |v88|, s20
	v_lshl_add_u64 v[96:97], s[6:7], 0, v[96:97]
	v_exp_f32_e32 v110, v98
	v_lshl_add_u64 v[98:99], v[96:97], 0, v[130:131]
	global_store_dwordx4 v[98:99], v[100:103], off nt
	global_store_dwordx4 v[98:99], v[106:109], off offset:16 nt
	v_add_f32_e32 v111, 1.0, v110
	v_mul_f32_e64 v100, |v92|, s20
	v_exp_f32_e32 v100, v100
	v_rcp_f32_e32 v111, v111
	v_cmp_nle_f32_e32 vcc, 0, v88
	v_add_f32_e32 v98, 1.0, v100
	v_rcp_f32_e32 v98, v98
	v_cndmask_b32_e32 v88, 1.0, v110, vcc
	v_mul_f32_e32 v88, v88, v111
	v_cmp_nle_f32_e32 vcc, 0, v92
	v_fma_f32 v88, v88, v141, v116
	v_log_f32_e32 v88, v88
	v_cndmask_b32_e32 v92, 1.0, v100, vcc
	v_mul_f32_e32 v92, v92, v98
	v_mul_f32_e64 v98, |v89|, s20
	v_exp_f32_e32 v98, v98
	v_mul_f32_e32 v88, 0x3f317218, v88
	v_fma_f32 v92, v92, v140, v112
	v_log_f32_e32 v99, v92
	v_max_f32_e32 v92, 0xc2700000, v88
	v_add_f32_e32 v88, 1.0, v98
	v_rcp_f32_e32 v88, v88
	v_cmp_nle_f32_e32 vcc, 0, v89
	v_mul_f32_e32 v99, 0x3f317218, v99
	s_nop 0
	v_cndmask_b32_e32 v89, 1.0, v98, vcc
	v_mul_f32_e32 v88, v89, v88
	v_mul_f32_e64 v89, |v93|, s20
	v_exp_f32_e32 v89, v89
	v_max_f32_e32 v98, 0xc2700000, v99
	v_cmp_nle_f32_e32 vcc, 0, v93
	v_fma_f32 v88, v88, v138, v117
	v_add_f32_e32 v99, 1.0, v89
	v_rcp_f32_e32 v99, v99
	v_cndmask_b32_e32 v89, 1.0, v89, vcc
	v_log_f32_e32 v88, v88
	v_mul_f32_e64 v93, |v90|, s20
	v_mul_f32_e32 v89, v89, v99
	v_fma_f32 v89, v89, v137, v113
	v_log_f32_e32 v89, v89
	v_exp_f32_e32 v100, v93
	v_mul_f32_e32 v88, 0x3f317218, v88
	v_max_f32_e32 v93, 0xc2700000, v88
	v_mul_f32_e32 v88, 0x3f317218, v89
	v_max_f32_e32 v99, 0xc2700000, v88
	v_add_f32_e32 v88, 1.0, v100
	v_mul_f32_e64 v89, |v94|, s20
	v_rcp_f32_e32 v88, v88
	v_exp_f32_e32 v89, v89
	v_cmp_nle_f32_e32 vcc, 0, v90
	s_nop 1
	v_cndmask_b32_e32 v90, 1.0, v100, vcc
	v_mul_f32_e32 v88, v90, v88
	v_add_f32_e32 v90, 1.0, v89
	v_rcp_f32_e32 v90, v90
	v_cmp_nle_f32_e32 vcc, 0, v94
	v_fma_f32 v88, v88, v136, v118
	v_log_f32_e32 v88, v88
	v_cndmask_b32_e32 v89, 1.0, v89, vcc
	v_mul_f32_e32 v89, v89, v90
	v_fma_f32 v89, v89, v135, v114
	v_mul_f32_e64 v90, |v91|, s20
	v_log_f32_e32 v89, v89
	v_exp_f32_e32 v90, v90
	v_mul_f32_e32 v88, 0x3f317218, v88
	v_max_f32_e32 v94, 0xc2700000, v88
	v_mul_f32_e32 v88, 0x3f317218, v89
	v_add_f32_e32 v89, 1.0, v90
	v_mul_f32_e64 v100, |v95|, s20
	v_rcp_f32_e32 v89, v89
	v_exp_f32_e32 v100, v100
	v_cmp_nle_f32_e32 vcc, 0, v91
	s_nop 1
	v_cndmask_b32_e32 v90, 1.0, v90, vcc
	v_mul_f32_e32 v89, v90, v89
	v_add_f32_e32 v90, 1.0, v100
	v_rcp_f32_e32 v90, v90
	v_cmp_nle_f32_e32 vcc, 0, v95
	v_fma_f32 v89, v89, v134, v119
	v_log_f32_e32 v89, v89
	v_cndmask_b32_e32 v91, 1.0, v100, vcc
	v_mul_f32_e32 v90, v91, v90
	v_fma_f32 v90, v90, v139, v115
	v_log_f32_e32 v90, v90
	v_max_f32_e32 v100, 0xc2700000, v88
	v_mul_f32_e32 v88, 0x3f317218, v89
	v_max_f32_e32 v95, 0xc2700000, v88
	v_mul_f32_e32 v88, 0x3f317218, v90
	v_mul_f32_e64 v89, |v80|, s20
	v_exp_f32_e32 v102, v89
	v_max_f32_e32 v101, 0xc2700000, v88
	v_lshl_add_u64 v[88:89], v[132:133], 0, s[4:5]
	v_lshl_add_u64 v[90:91], v[88:89], 0, v[130:131]
	global_store_dwordx4 v[90:91], v[92:95], off nt
	v_add_f32_e32 v103, 1.0, v102
	v_rcp_f32_e32 v103, v103
	v_mul_f32_e64 v92, |v84|, s20
	v_exp_f32_e32 v92, v92
	global_store_dwordx4 v[90:91], v[98:101], off offset:16 nt
	v_cmp_nle_f32_e32 vcc, 0, v80
	s_mov_b64 s[4:5], 0x48000
	v_add_f32_e32 v90, 1.0, v92
	v_rcp_f32_e32 v90, v90
	v_cndmask_b32_e32 v80, 1.0, v102, vcc
	v_mul_f32_e32 v80, v80, v103
	v_cmp_nle_f32_e32 vcc, 0, v84
	v_fma_f32 v80, v80, v141, v116
	v_log_f32_e32 v80, v80
	v_cndmask_b32_e32 v84, 1.0, v92, vcc
	v_mul_f32_e32 v84, v84, v90
	v_mul_f32_e64 v90, |v81|, s20
	v_exp_f32_e32 v90, v90
	v_mul_f32_e32 v80, 0x3f317218, v80
	v_fma_f32 v84, v84, v140, v112
	v_log_f32_e32 v91, v84
	v_max_f32_e32 v84, 0xc2700000, v80
	v_add_f32_e32 v80, 1.0, v90
	v_rcp_f32_e32 v80, v80
	v_cmp_nle_f32_e32 vcc, 0, v81
	v_mul_f32_e32 v91, 0x3f317218, v91
	s_nop 0
	v_cndmask_b32_e32 v81, 1.0, v90, vcc
	v_mul_f32_e32 v80, v81, v80
	v_mul_f32_e64 v81, |v85|, s20
	v_exp_f32_e32 v81, v81
	v_max_f32_e32 v90, 0xc2700000, v91
	v_cmp_nle_f32_e32 vcc, 0, v85
	v_fma_f32 v80, v80, v138, v117
	v_add_f32_e32 v91, 1.0, v81
	v_rcp_f32_e32 v91, v91
	v_cndmask_b32_e32 v81, 1.0, v81, vcc
	v_log_f32_e32 v80, v80
	v_mul_f32_e64 v85, |v82|, s20
	v_mul_f32_e32 v81, v81, v91
	v_fma_f32 v81, v81, v137, v113
	v_log_f32_e32 v81, v81
	v_exp_f32_e32 v92, v85
	v_mul_f32_e32 v80, 0x3f317218, v80
	v_max_f32_e32 v85, 0xc2700000, v80
	v_mul_f32_e32 v80, 0x3f317218, v81
	v_max_f32_e32 v91, 0xc2700000, v80
	v_add_f32_e32 v80, 1.0, v92
	v_mul_f32_e64 v81, |v86|, s20
	v_rcp_f32_e32 v80, v80
	v_exp_f32_e32 v81, v81
	v_cmp_nle_f32_e32 vcc, 0, v82
	s_nop 1
	v_cndmask_b32_e32 v82, 1.0, v92, vcc
	v_mul_f32_e32 v80, v82, v80
	v_add_f32_e32 v82, 1.0, v81
	v_rcp_f32_e32 v82, v82
	v_cmp_nle_f32_e32 vcc, 0, v86
	v_fma_f32 v80, v80, v136, v118
	v_log_f32_e32 v80, v80
	v_cndmask_b32_e32 v81, 1.0, v81, vcc
	v_mul_f32_e32 v81, v81, v82
	v_fma_f32 v81, v81, v135, v114
	v_mul_f32_e64 v82, |v83|, s20
	v_log_f32_e32 v81, v81
	v_exp_f32_e32 v82, v82
	v_mul_f32_e32 v80, 0x3f317218, v80
	v_max_f32_e32 v86, 0xc2700000, v80
	v_mul_f32_e32 v80, 0x3f317218, v81
	v_add_f32_e32 v81, 1.0, v82
	v_mul_f32_e64 v92, |v87|, s20
	v_rcp_f32_e32 v81, v81
	v_exp_f32_e32 v92, v92
	v_cmp_nle_f32_e32 vcc, 0, v83
	s_nop 1
	v_cndmask_b32_e32 v82, 1.0, v82, vcc
	v_mul_f32_e32 v81, v82, v81
	v_add_f32_e32 v82, 1.0, v92
	v_rcp_f32_e32 v82, v82
	v_cmp_nle_f32_e32 vcc, 0, v87
	v_fma_f32 v81, v81, v134, v119
	v_log_f32_e32 v81, v81
	v_cndmask_b32_e32 v83, 1.0, v92, vcc
	v_mul_f32_e32 v82, v83, v82
	v_fma_f32 v82, v82, v139, v115
	v_log_f32_e32 v82, v82
	v_max_f32_e32 v92, 0xc2700000, v80
	v_mul_f32_e32 v80, 0x3f317218, v81
	v_max_f32_e32 v87, 0xc2700000, v80
	v_mul_f32_e32 v80, 0x3f317218, v82
	v_mul_f32_e64 v81, |v72|, s20
	v_exp_f32_e32 v94, v81
	v_max_f32_e32 v93, 0xc2700000, v80
	v_lshl_add_u64 v[80:81], v[132:133], 0, s[4:5]
	v_lshl_add_u64 v[82:83], v[80:81], 0, v[130:131]
	global_store_dwordx4 v[82:83], v[84:87], off nt
	v_add_f32_e32 v95, 1.0, v94
	v_rcp_f32_e32 v95, v95
	v_mul_f32_e64 v84, |v76|, s20
	v_exp_f32_e32 v84, v84
	global_store_dwordx4 v[82:83], v[90:93], off offset:16 nt
	v_cmp_nle_f32_e32 vcc, 0, v72
	s_mov_b64 s[4:5], 0x50000
	v_add_f32_e32 v82, 1.0, v84
	v_rcp_f32_e32 v82, v82
	v_cndmask_b32_e32 v72, 1.0, v94, vcc
	v_mul_f32_e32 v72, v72, v95
	v_cmp_nle_f32_e32 vcc, 0, v76
	v_fma_f32 v72, v72, v141, v116
	v_log_f32_e32 v72, v72
	v_cndmask_b32_e32 v76, 1.0, v84, vcc
	v_mul_f32_e32 v76, v76, v82
	v_mul_f32_e64 v82, |v73|, s20
	v_exp_f32_e32 v82, v82
	v_mul_f32_e32 v72, 0x3f317218, v72
	v_fma_f32 v76, v76, v140, v112
	v_log_f32_e32 v83, v76
	v_max_f32_e32 v76, 0xc2700000, v72
	v_add_f32_e32 v72, 1.0, v82
	v_rcp_f32_e32 v72, v72
	v_cmp_nle_f32_e32 vcc, 0, v73
	v_mul_f32_e32 v83, 0x3f317218, v83
	s_nop 0
	v_cndmask_b32_e32 v73, 1.0, v82, vcc
	v_mul_f32_e32 v72, v73, v72
	v_mul_f32_e64 v73, |v77|, s20
	v_exp_f32_e32 v73, v73
	v_max_f32_e32 v82, 0xc2700000, v83
	v_cmp_nle_f32_e32 vcc, 0, v77
	v_fma_f32 v72, v72, v138, v117
	v_add_f32_e32 v83, 1.0, v73
	v_rcp_f32_e32 v83, v83
	v_cndmask_b32_e32 v73, 1.0, v73, vcc
	v_log_f32_e32 v72, v72
	v_mul_f32_e64 v77, |v74|, s20
	v_mul_f32_e32 v73, v73, v83
	v_fma_f32 v73, v73, v137, v113
	v_log_f32_e32 v73, v73
	v_exp_f32_e32 v84, v77
	v_mul_f32_e32 v72, 0x3f317218, v72
	v_max_f32_e32 v77, 0xc2700000, v72
	v_mul_f32_e32 v72, 0x3f317218, v73
	v_max_f32_e32 v83, 0xc2700000, v72
	v_add_f32_e32 v72, 1.0, v84
	v_mul_f32_e64 v73, |v78|, s20
	v_rcp_f32_e32 v72, v72
	v_exp_f32_e32 v73, v73
	v_cmp_nle_f32_e32 vcc, 0, v74
	s_nop 1
	v_cndmask_b32_e32 v74, 1.0, v84, vcc
	v_mul_f32_e32 v72, v74, v72
	v_add_f32_e32 v74, 1.0, v73
	v_rcp_f32_e32 v74, v74
	v_cmp_nle_f32_e32 vcc, 0, v78
	v_fma_f32 v72, v72, v136, v118
	v_log_f32_e32 v72, v72
	v_cndmask_b32_e32 v73, 1.0, v73, vcc
	v_mul_f32_e32 v73, v73, v74
	v_fma_f32 v73, v73, v135, v114
	v_mul_f32_e64 v74, |v75|, s20
	v_log_f32_e32 v73, v73
	v_exp_f32_e32 v74, v74
	v_mul_f32_e32 v72, 0x3f317218, v72
	v_max_f32_e32 v78, 0xc2700000, v72
	v_mul_f32_e32 v72, 0x3f317218, v73
	v_add_f32_e32 v73, 1.0, v74
	v_mul_f32_e64 v84, |v79|, s20
	v_rcp_f32_e32 v73, v73
	v_exp_f32_e32 v84, v84
	v_cmp_nle_f32_e32 vcc, 0, v75
	s_nop 1
	v_cndmask_b32_e32 v74, 1.0, v74, vcc
	v_mul_f32_e32 v73, v74, v73
	v_add_f32_e32 v74, 1.0, v84
	v_rcp_f32_e32 v74, v74
	v_cmp_nle_f32_e32 vcc, 0, v79
	v_fma_f32 v73, v73, v134, v119
	v_log_f32_e32 v73, v73
	v_cndmask_b32_e32 v75, 1.0, v84, vcc
	v_mul_f32_e32 v74, v75, v74
	v_fma_f32 v74, v74, v139, v115
	v_log_f32_e32 v74, v74
	v_max_f32_e32 v84, 0xc2700000, v72
	v_mul_f32_e32 v72, 0x3f317218, v73
	v_max_f32_e32 v79, 0xc2700000, v72
	v_mul_f32_e32 v72, 0x3f317218, v74
	v_mul_f32_e64 v73, |v64|, s20
	v_lshl_add_u64 v[74:75], v[132:133], 0, s[4:5]
	v_exp_f32_e32 v86, v73
	v_max_f32_e32 v85, 0xc2700000, v72
	v_lshl_add_u64 v[72:73], v[74:75], 0, v[130:131]
	global_store_dwordx4 v[72:73], v[76:79], off nt
	global_store_dwordx4 v[72:73], v[82:85], off offset:16 nt
	v_cmp_nle_f32_e32 vcc, 0, v64
	v_mul_f32_e64 v76, |v68|, s20
	v_exp_f32_e32 v76, v76
	v_cndmask_b32_e32 v64, 1.0, v86, vcc
	v_cmp_nle_f32_e32 vcc, 0, v68
	v_add_f32_e32 v87, 1.0, v86
	v_add_f32_e32 v72, 1.0, v76
	v_rcp_f32_e32 v72, v72
	v_cndmask_b32_e32 v68, 1.0, v76, vcc
	v_cmp_nle_f32_e32 vcc, 0, v65
	v_mul_f32_e64 v76, |v70|, s20
	v_mul_f32_e32 v68, v68, v72
	v_mul_f32_e64 v72, |v65|, s20
	v_exp_f32_e32 v72, v72
	v_exp_f32_e32 v76, v76
	v_rcp_f32_e32 v87, v87
	v_fma_f32 v68, v68, v140, v112
	v_add_f32_e32 v73, 1.0, v72
	v_cndmask_b32_e32 v65, 1.0, v72, vcc
	v_mul_f32_e64 v72, |v69|, s20
	v_rcp_f32_e32 v73, v73
	v_exp_f32_e32 v72, v72
	v_cmp_nle_f32_e32 vcc, 0, v69
	v_mul_f32_e32 v64, v64, v87
	v_mul_f32_e32 v65, v65, v73
	v_add_f32_e32 v73, 1.0, v72
	v_cndmask_b32_e32 v69, 1.0, v72, vcc
	v_mul_f32_e64 v72, |v66|, s20
	v_rcp_f32_e32 v73, v73
	v_exp_f32_e32 v72, v72
	v_cmp_nle_f32_e32 vcc, 0, v66
	v_fma_f32 v64, v64, v141, v116
	v_mul_f32_e32 v69, v69, v73
	v_add_f32_e32 v73, 1.0, v72
	v_cndmask_b32_e32 v66, 1.0, v72, vcc
	v_add_f32_e32 v72, 1.0, v76
	v_rcp_f32_e32 v72, v72
	v_cmp_nle_f32_e32 vcc, 0, v70
	v_rcp_f32_e32 v73, v73
	v_fma_f32 v65, v65, v138, v117
	v_cndmask_b32_e32 v70, 1.0, v76, vcc
	v_mul_f32_e32 v70, v70, v72
	v_mul_f32_e64 v72, |v67|, s20
	v_exp_f32_e32 v72, v72
	v_mul_f32_e32 v66, v66, v73
	v_mul_f32_e64 v76, |v71|, s20
	v_exp_f32_e32 v76, v76
	v_add_f32_e32 v73, 1.0, v72
	v_rcp_f32_e32 v73, v73
	v_cmp_nle_f32_e32 vcc, 0, v67
	v_fma_f32 v66, v66, v136, v118
	v_log_f32_e32 v64, v64
	v_cndmask_b32_e32 v67, 1.0, v72, vcc
	v_mul_f32_e32 v67, v67, v73
	v_fmac_f32_e32 v119, v67, v134
	v_add_f32_e32 v67, 1.0, v76
	v_rcp_f32_e32 v67, v67
	v_cmp_nle_f32_e32 vcc, 0, v71
	v_log_f32_e32 v65, v65
	v_fma_f32 v69, v69, v137, v113
	v_cndmask_b32_e32 v71, 1.0, v76, vcc
	v_mul_f32_e32 v67, v71, v67
	v_log_f32_e32 v66, v66
	v_fma_f32 v70, v70, v135, v114
	v_log_f32_e32 v72, v119
	v_fmac_f32_e32 v115, v67, v139
	v_log_f32_e32 v68, v68
	v_log_f32_e32 v69, v69
	v_log_f32_e32 v70, v70
	v_log_f32_e32 v71, v115
	s_mov_b64 s[4:5], 0x58000
	v_mul_f32_e32 v64, 0x3f317218, v64
	v_mul_f32_e32 v65, 0x3f317218, v65
	v_mul_f32_e32 v66, 0x3f317218, v66
	v_mul_f32_e32 v67, 0x3f317218, v72
	v_lshl_add_u64 v[72:73], v[132:133], 0, s[4:5]
	v_max_f32_e32 v64, 0xc2700000, v64
	v_mul_f32_e32 v68, 0x3f317218, v68
	v_max_f32_e32 v65, 0xc2700000, v65
	v_mul_f32_e32 v69, 0x3f317218, v69
	v_max_f32_e32 v66, 0xc2700000, v66
	v_mul_f32_e32 v70, 0x3f317218, v70
	v_max_f32_e32 v67, 0xc2700000, v67
	v_mul_f32_e32 v71, 0x3f317218, v71
	v_lshl_add_u64 v[76:77], v[72:73], 0, v[130:131]
	v_max_f32_e32 v68, 0xc2700000, v68
	v_max_f32_e32 v69, 0xc2700000, v69
	v_max_f32_e32 v70, 0xc2700000, v70
	v_max_f32_e32 v71, 0xc2700000, v71
	global_store_dwordx4 v[76:77], v[64:67], off nt
	global_store_dwordx4 v[76:77], v[68:71], off offset:16 nt
	v_mul_f32_e64 v78, |v60|, s20
	v_add_u32_e32 v64, 0xfffffe80, v170
	v_ashrrev_i32_e32 v65, 31, v64
	v_lshlrev_b64 v[76:77], 2, v[64:65]
	v_lshl_add_u64 v[64:65], s[48:49], 0, v[76:77]
	global_load_dwordx4 v[68:71], v[64:65], off
	s_nop 0
	global_load_dwordx4 v[64:67], v[64:65], off offset:16
	v_exp_f32_e32 v78, v78
	v_cmp_nle_f32_e32 vcc, 0, v60
	v_lshl_add_u64 v[116:117], v[72:73], 0, v[76:77]
	v_add_f32_e32 v79, 1.0, v78
	v_rcp_f32_e32 v79, v79
	v_cndmask_b32_e32 v60, 1.0, v78, vcc
	v_cmp_nle_f32_e32 vcc, 0, v56
	v_mul_f32_e32 v78, v60, v79
	v_mul_f32_e64 v79, |v56|, s20
	v_exp_f32_e32 v79, v79
	s_waitcnt vmcnt(1)
	v_sub_f32_e32 v60, 1.0, v68
	v_add_f32_e32 v82, 1.0, v79
	v_rcp_f32_e32 v82, v82
	v_fma_f32 v78, v78, v60, v68
	v_cndmask_b32_e32 v56, 1.0, v79, vcc
	v_log_f32_e32 v78, v78
	v_mul_f32_e32 v79, v56, v82
	v_mul_f32_e64 v82, |v61|, s20
	v_exp_f32_e32 v83, v82
	v_mul_f32_e32 v78, 0x3f317218, v78
	s_waitcnt vmcnt(0)
	v_sub_f32_e32 v56, 1.0, v64
	v_fma_f32 v79, v79, v56, v64
	v_max_f32_e32 v82, 0xc2700000, v78
	v_add_f32_e32 v78, 1.0, v83
	v_cmp_nle_f32_e32 vcc, 0, v61
	v_log_f32_e32 v79, v79
	v_rcp_f32_e32 v78, v78
	v_cndmask_b32_e32 v61, 1.0, v83, vcc
	v_mul_f32_e64 v83, |v57|, s20
	v_exp_f32_e32 v83, v83
	v_mul_f32_e32 v79, 0x3f317218, v79
	v_mul_f32_e32 v78, v61, v78
	v_sub_f32_e32 v61, 1.0, v69
	v_fma_f32 v78, v78, v61, v69
	v_max_f32_e32 v90, 0xc2700000, v79
	v_add_f32_e32 v79, 1.0, v83
	v_log_f32_e32 v78, v78
	v_rcp_f32_e32 v79, v79
	v_cmp_nle_f32_e32 vcc, 0, v57
	v_mul_f32_e32 v84, 0x3f317218, v78
	s_nop 0
	v_cndmask_b32_e32 v57, 1.0, v83, vcc
	v_mul_f32_e32 v57, v57, v79
	v_sub_f32_e32 v78, 1.0, v65
	v_mul_f32_e64 v79, |v62|, s20
	v_exp_f32_e32 v79, v79
	v_fma_f32 v57, v57, v78, v65
	v_log_f32_e32 v57, v57
	v_max_f32_e32 v83, 0xc2700000, v84
	v_add_f32_e32 v84, 1.0, v79
	v_cmp_nle_f32_e32 vcc, 0, v62
	v_rcp_f32_e32 v84, v84
	v_mul_f32_e32 v85, 0x3f317218, v57
	v_cndmask_b32_e32 v57, 1.0, v79, vcc
	v_mul_f32_e64 v79, |v58|, s20
	v_exp_f32_e32 v79, v79
	v_mul_f32_e32 v62, v57, v84
	v_sub_f32_e32 v57, 1.0, v70
	v_fma_f32 v62, v62, v57, v70
	v_add_f32_e32 v84, 1.0, v79
	v_log_f32_e32 v62, v62
	v_rcp_f32_e32 v84, v84
	v_cmp_nle_f32_e32 vcc, 0, v58
	v_max_f32_e32 v91, 0xc2700000, v85
	v_mul_f32_e32 v85, 0x3f317218, v62
	v_cndmask_b32_e32 v58, 1.0, v79, vcc
	v_mul_f32_e32 v58, v58, v84
	v_sub_f32_e32 v62, 1.0, v66
	v_mul_f32_e64 v79, |v63|, s20
	v_fma_f32 v58, v58, v62, v66
	v_exp_f32_e32 v79, v79
	v_log_f32_e32 v58, v58
	v_cmp_nle_f32_e32 vcc, 0, v63
	v_max_f32_e32 v84, 0xc2700000, v85
	v_add_f32_e32 v85, 1.0, v79
	v_mul_f32_e32 v86, 0x3f317218, v58
	v_cndmask_b32_e32 v58, 1.0, v79, vcc
	v_mul_f32_e64 v79, |v59|, s20
	v_rcp_f32_e32 v85, v85
	v_exp_f32_e32 v79, v79
	v_cmp_nle_f32_e32 vcc, 0, v59
	v_max_f32_e32 v92, 0xc2700000, v86
	v_mul_f32_e32 v63, v58, v85
	v_sub_f32_e32 v58, 1.0, v71
	v_add_f32_e32 v85, 1.0, v79
	v_fma_f32 v63, v63, v58, v71
	v_rcp_f32_e32 v85, v85
	v_log_f32_e32 v63, v63
	v_cndmask_b32_e32 v59, 1.0, v79, vcc
	v_cmp_nle_f32_e32 vcc, 0, v52
	v_mul_f32_e32 v79, v59, v85
	v_sub_f32_e32 v59, 1.0, v67
	v_mul_f32_e32 v63, 0x3f317218, v63
	v_fma_f32 v79, v79, v59, v67
	v_log_f32_e32 v79, v79
	v_max_f32_e32 v85, 0xc2700000, v63
	v_mul_f32_e64 v63, |v52|, s20
	v_exp_f32_e32 v63, v63
	v_mul_f32_e32 v79, 0x3f317218, v79
	v_max_f32_e32 v93, 0xc2700000, v79
	v_lshl_add_u64 v[86:87], v[132:133], 0, v[76:77]
	v_add_f32_e32 v79, 1.0, v63
	v_cndmask_b32_e32 v52, 1.0, v63, vcc
	v_mul_f32_e64 v63, |v48|, s20
	v_rcp_f32_e32 v79, v79
	v_exp_f32_e32 v63, v63
	v_cmp_nle_f32_e32 vcc, 0, v48
	global_store_dwordx4 v[86:87], v[82:85], off
	v_mul_f32_e32 v52, v52, v79
	v_add_f32_e32 v79, 1.0, v63
	v_fma_f32 v52, v52, v60, v68
	v_rcp_f32_e32 v79, v79
	v_log_f32_e32 v52, v52
	v_cndmask_b32_e32 v48, 1.0, v63, vcc
	v_mul_f32_e64 v63, |v53|, s20
	v_exp_f32_e32 v63, v63
	v_mul_f32_e32 v48, v48, v79
	v_mul_f32_e32 v52, 0x3f317218, v52
	v_fma_f32 v48, v48, v56, v64
	v_log_f32_e32 v79, v48
	v_max_f32_e32 v48, 0xc2700000, v52
	v_add_f32_e32 v52, 1.0, v63
	v_rcp_f32_e32 v52, v52
	v_cmp_nle_f32_e32 vcc, 0, v53
	v_mul_f32_e32 v79, 0x3f317218, v79
	v_lshl_add_u64 v[82:83], v[120:121], 0, v[76:77]
	v_cndmask_b32_e32 v53, 1.0, v63, vcc
	v_mul_f32_e32 v52, v53, v52
	v_mul_f32_e64 v53, |v49|, s20
	v_exp_f32_e32 v53, v53
	v_fma_f32 v52, v52, v61, v69
	v_log_f32_e32 v63, v52
	v_max_f32_e32 v52, 0xc2700000, v79
	v_add_f32_e32 v79, 1.0, v53
	v_rcp_f32_e32 v79, v79
	v_cmp_nle_f32_e32 vcc, 0, v49
	v_mul_f32_e32 v63, 0x3f317218, v63
	global_store_dwordx4 v[86:87], v[90:93], off offset:16
	v_cndmask_b32_e32 v49, 1.0, v53, vcc
	v_mul_f32_e64 v53, |v54|, s20
	v_exp_f32_e32 v53, v53
	v_mul_f32_e32 v49, v49, v79
	v_fma_f32 v49, v49, v78, v65
	v_log_f32_e32 v79, v49
	v_max_f32_e32 v49, 0xc2700000, v63
	v_add_f32_e32 v63, 1.0, v53
	v_rcp_f32_e32 v63, v63
	v_cmp_nle_f32_e32 vcc, 0, v54
	v_mul_f32_e64 v54, |v50|, s20
	v_exp_f32_e32 v54, v54
	v_cndmask_b32_e32 v53, 1.0, v53, vcc
	v_mul_f32_e32 v53, v53, v63
	v_mul_f32_e32 v79, 0x3f317218, v79
	v_fma_f32 v53, v53, v57, v70
	v_log_f32_e32 v63, v53
	v_max_f32_e32 v53, 0xc2700000, v79
	v_add_f32_e32 v79, 1.0, v54
	v_rcp_f32_e32 v79, v79
	v_cmp_nle_f32_e32 vcc, 0, v50
	v_mul_f32_e32 v63, 0x3f317218, v63
	s_nop 0
	v_cndmask_b32_e32 v50, 1.0, v54, vcc
	v_mul_f32_e64 v54, |v55|, s20
	v_exp_f32_e32 v54, v54
	v_mul_f32_e32 v50, v50, v79
	v_fma_f32 v50, v50, v62, v66
	v_log_f32_e32 v79, v50
	v_max_f32_e32 v50, 0xc2700000, v63
	v_add_f32_e32 v63, 1.0, v54
	v_rcp_f32_e32 v63, v63
	v_cmp_nle_f32_e32 vcc, 0, v55
	v_mul_f32_e64 v55, |v51|, s20
	v_exp_f32_e32 v55, v55
	v_cndmask_b32_e32 v54, 1.0, v54, vcc
	v_mul_f32_e32 v54, v54, v63
	v_mul_f32_e32 v79, 0x3f317218, v79
	v_fma_f32 v54, v54, v58, v71
	v_log_f32_e32 v63, v54
	v_max_f32_e32 v54, 0xc2700000, v79
	v_add_f32_e32 v79, 1.0, v55
	v_rcp_f32_e32 v79, v79
	v_cmp_nle_f32_e32 vcc, 0, v51
	v_mul_f32_e32 v63, 0x3f317218, v63
	s_nop 0
	v_cndmask_b32_e32 v51, 1.0, v55, vcc
	v_mul_f32_e32 v51, v51, v79
	v_fma_f32 v51, v51, v59, v67
	v_log_f32_e32 v55, v51
	v_max_f32_e32 v51, 0xc2700000, v63
	v_mul_f32_e64 v63, |v44|, s20
	v_exp_f32_e32 v63, v63
	global_store_dwordx4 v[82:83], v[48:51], off
	v_cmp_nle_f32_e32 vcc, 0, v44
	v_mul_f32_e32 v55, 0x3f317218, v55
	v_add_f32_e32 v79, 1.0, v63
	v_mul_f32_e64 v48, |v40|, s20
	v_rcp_f32_e32 v79, v79
	v_exp_f32_e32 v48, v48
	v_cndmask_b32_e32 v44, 1.0, v63, vcc
	v_cmp_nle_f32_e32 vcc, 0, v40
	v_mul_f32_e32 v44, v44, v79
	v_add_f32_e32 v49, 1.0, v48
	v_fma_f32 v44, v44, v60, v68
	v_rcp_f32_e32 v49, v49
	v_log_f32_e32 v44, v44
	v_cndmask_b32_e32 v40, 1.0, v48, vcc
	v_mul_f32_e64 v48, |v45|, s20
	v_exp_f32_e32 v48, v48
	v_mul_f32_e32 v40, v40, v49
	v_mul_f32_e32 v44, 0x3f317218, v44
	v_fma_f32 v40, v40, v56, v64
	v_log_f32_e32 v49, v40
	v_max_f32_e32 v40, 0xc2700000, v44
	v_add_f32_e32 v44, 1.0, v48
	v_rcp_f32_e32 v44, v44
	v_cmp_nle_f32_e32 vcc, 0, v45
	v_mul_f32_e32 v49, 0x3f317218, v49
	v_max_f32_e32 v55, 0xc2700000, v55
	v_cndmask_b32_e32 v45, 1.0, v48, vcc
	v_mul_f32_e32 v44, v45, v44
	v_mul_f32_e64 v45, |v41|, s20
	v_exp_f32_e32 v45, v45
	v_fma_f32 v44, v44, v61, v69
	v_log_f32_e32 v48, v44
	v_max_f32_e32 v44, 0xc2700000, v49
	v_add_f32_e32 v49, 1.0, v45
	v_rcp_f32_e32 v49, v49
	v_cmp_nle_f32_e32 vcc, 0, v41
	v_mul_f32_e32 v48, 0x3f317218, v48
	global_store_dwordx4 v[82:83], v[52:55], off offset:16
	v_cndmask_b32_e32 v41, 1.0, v45, vcc
	v_mul_f32_e64 v45, |v46|, s20
	v_exp_f32_e32 v45, v45
	v_mul_f32_e32 v41, v41, v49
	v_fma_f32 v41, v41, v78, v65
	v_log_f32_e32 v49, v41
	v_max_f32_e32 v41, 0xc2700000, v48
	v_add_f32_e32 v48, 1.0, v45
	v_rcp_f32_e32 v48, v48
	v_cmp_nle_f32_e32 vcc, 0, v46
	v_mul_f32_e64 v46, |v42|, s20
	v_exp_f32_e32 v46, v46
	v_cndmask_b32_e32 v45, 1.0, v45, vcc
	v_mul_f32_e32 v45, v45, v48
	v_mul_f32_e32 v49, 0x3f317218, v49
	v_fma_f32 v45, v45, v57, v70
	v_log_f32_e32 v48, v45
	v_max_f32_e32 v45, 0xc2700000, v49
	v_add_f32_e32 v49, 1.0, v46
	v_rcp_f32_e32 v49, v49
	v_cmp_nle_f32_e32 vcc, 0, v42
	v_mul_f32_e32 v48, 0x3f317218, v48
	s_nop 0
	v_cndmask_b32_e32 v42, 1.0, v46, vcc
	v_mul_f32_e64 v46, |v47|, s20
	v_exp_f32_e32 v46, v46
	v_mul_f32_e32 v42, v42, v49
	v_fma_f32 v42, v42, v62, v66
	v_log_f32_e32 v49, v42
	v_max_f32_e32 v42, 0xc2700000, v48
	v_add_f32_e32 v48, 1.0, v46
	v_rcp_f32_e32 v48, v48
	v_cmp_nle_f32_e32 vcc, 0, v47
	v_mul_f32_e64 v47, |v43|, s20
	v_exp_f32_e32 v47, v47
	v_cndmask_b32_e32 v46, 1.0, v46, vcc
	v_mul_f32_e32 v46, v46, v48
	v_mul_f32_e32 v49, 0x3f317218, v49
	v_fma_f32 v46, v46, v58, v71
	v_log_f32_e32 v48, v46
	v_max_f32_e32 v46, 0xc2700000, v49
	v_add_f32_e32 v49, 1.0, v47
	v_rcp_f32_e32 v49, v49
	v_cmp_nle_f32_e32 vcc, 0, v43
	v_mul_f32_e32 v48, 0x3f317218, v48
	s_nop 0
	v_cndmask_b32_e32 v43, 1.0, v47, vcc
	v_mul_f32_e32 v43, v43, v49
	v_fma_f32 v43, v43, v59, v67
	v_log_f32_e32 v47, v43
	v_max_f32_e32 v43, 0xc2700000, v48
	v_mul_f32_e64 v48, |v36|, s20
	v_exp_f32_e32 v50, v48
	v_lshl_add_u64 v[48:49], v[104:105], 0, v[76:77]
	global_store_dwordx4 v[48:49], v[40:43], off
	v_cmp_nle_f32_e32 vcc, 0, v36
	v_add_f32_e32 v51, 1.0, v50
	v_mul_f32_e64 v40, |v32|, s20
	v_rcp_f32_e32 v51, v51
	v_exp_f32_e32 v40, v40
	v_cndmask_b32_e32 v36, 1.0, v50, vcc
	v_cmp_nle_f32_e32 vcc, 0, v32
	v_mul_f32_e32 v36, v36, v51
	v_add_f32_e32 v41, 1.0, v40
	v_fma_f32 v36, v36, v60, v68
	v_rcp_f32_e32 v41, v41
	v_log_f32_e32 v36, v36
	v_cndmask_b32_e32 v32, 1.0, v40, vcc
	v_mul_f32_e64 v40, |v37|, s20
	v_exp_f32_e32 v40, v40
	v_mul_f32_e32 v32, v32, v41
	v_mul_f32_e32 v36, 0x3f317218, v36
	v_fma_f32 v32, v32, v56, v64
	v_log_f32_e32 v41, v32
	v_max_f32_e32 v32, 0xc2700000, v36
	v_add_f32_e32 v36, 1.0, v40
	v_rcp_f32_e32 v36, v36
	v_cmp_nle_f32_e32 vcc, 0, v37
	v_mul_f32_e32 v41, 0x3f317218, v41
	v_mul_f32_e32 v47, 0x3f317218, v47
	v_cndmask_b32_e32 v37, 1.0, v40, vcc
	v_mul_f32_e32 v36, v37, v36
	v_mul_f32_e64 v37, |v33|, s20
	v_exp_f32_e32 v37, v37
	v_fma_f32 v36, v36, v61, v69
	v_log_f32_e32 v40, v36
	v_max_f32_e32 v36, 0xc2700000, v41
	v_add_f32_e32 v41, 1.0, v37
	v_rcp_f32_e32 v41, v41
	v_cmp_nle_f32_e32 vcc, 0, v33
	v_mul_f32_e32 v40, 0x3f317218, v40
	v_max_f32_e32 v47, 0xc2700000, v47
	v_cndmask_b32_e32 v33, 1.0, v37, vcc
	v_mul_f32_e64 v37, |v38|, s20
	v_exp_f32_e32 v37, v37
	v_mul_f32_e32 v33, v33, v41
	v_fma_f32 v33, v33, v78, v65
	v_log_f32_e32 v41, v33
	v_max_f32_e32 v33, 0xc2700000, v40
	v_add_f32_e32 v40, 1.0, v37
	v_rcp_f32_e32 v40, v40
	v_cmp_nle_f32_e32 vcc, 0, v38
	v_mul_f32_e64 v38, |v34|, s20
	v_exp_f32_e32 v38, v38
	v_cndmask_b32_e32 v37, 1.0, v37, vcc
	v_mul_f32_e32 v37, v37, v40
	v_mul_f32_e32 v41, 0x3f317218, v41
	v_fma_f32 v37, v37, v57, v70
	v_log_f32_e32 v40, v37
	v_max_f32_e32 v37, 0xc2700000, v41
	v_add_f32_e32 v41, 1.0, v38
	v_rcp_f32_e32 v41, v41
	v_cmp_nle_f32_e32 vcc, 0, v34
	v_mul_f32_e32 v40, 0x3f317218, v40
	global_store_dwordx4 v[48:49], v[44:47], off offset:16
	v_cndmask_b32_e32 v34, 1.0, v38, vcc
	v_mul_f32_e64 v38, |v39|, s20
	v_exp_f32_e32 v38, v38
	v_mul_f32_e32 v34, v34, v41
	v_fma_f32 v34, v34, v62, v66
	v_log_f32_e32 v41, v34
	v_max_f32_e32 v34, 0xc2700000, v40
	v_add_f32_e32 v40, 1.0, v38
	v_rcp_f32_e32 v40, v40
	v_cmp_nle_f32_e32 vcc, 0, v39
	v_mul_f32_e64 v39, |v35|, s20
	v_exp_f32_e32 v39, v39
	v_cndmask_b32_e32 v38, 1.0, v38, vcc
	v_mul_f32_e32 v38, v38, v40
	v_mul_f32_e32 v41, 0x3f317218, v41
	v_fma_f32 v38, v38, v58, v71
	v_log_f32_e32 v40, v38
	v_max_f32_e32 v38, 0xc2700000, v41
	v_add_f32_e32 v41, 1.0, v39
	v_rcp_f32_e32 v41, v41
	v_cmp_nle_f32_e32 vcc, 0, v35
	v_mul_f32_e32 v40, 0x3f317218, v40
	s_nop 0
	v_cndmask_b32_e32 v35, 1.0, v39, vcc
	v_mul_f32_e32 v35, v35, v41
	v_fma_f32 v35, v35, v59, v67
	v_log_f32_e32 v39, v35
	v_max_f32_e32 v35, 0xc2700000, v40
	v_mul_f32_e64 v40, |v28|, s20
	v_exp_f32_e32 v42, v40
	v_lshl_add_u64 v[40:41], v[96:97], 0, v[76:77]
	global_store_dwordx4 v[40:41], v[32:35], off
	v_cmp_nle_f32_e32 vcc, 0, v28
	v_add_f32_e32 v43, 1.0, v42
	v_mul_f32_e64 v32, |v24|, s20
	v_rcp_f32_e32 v43, v43
	v_exp_f32_e32 v32, v32
	v_cndmask_b32_e32 v28, 1.0, v42, vcc
	v_cmp_nle_f32_e32 vcc, 0, v24
	v_mul_f32_e32 v28, v28, v43
	v_add_f32_e32 v33, 1.0, v32
	v_fma_f32 v28, v28, v60, v68
	v_rcp_f32_e32 v33, v33
	v_log_f32_e32 v28, v28
	v_cndmask_b32_e32 v24, 1.0, v32, vcc
	v_mul_f32_e64 v32, |v29|, s20
	v_exp_f32_e32 v32, v32
	v_mul_f32_e32 v24, v24, v33
	v_mul_f32_e32 v28, 0x3f317218, v28
	v_fma_f32 v24, v24, v56, v64
	v_log_f32_e32 v33, v24
	v_max_f32_e32 v24, 0xc2700000, v28
	v_add_f32_e32 v28, 1.0, v32
	v_rcp_f32_e32 v28, v28
	v_cmp_nle_f32_e32 vcc, 0, v29
	v_mul_f32_e32 v33, 0x3f317218, v33
	v_mul_f32_e32 v39, 0x3f317218, v39
	v_cndmask_b32_e32 v29, 1.0, v32, vcc
	v_mul_f32_e32 v28, v29, v28
	v_mul_f32_e64 v29, |v25|, s20
	v_exp_f32_e32 v29, v29
	v_fma_f32 v28, v28, v61, v69
	v_log_f32_e32 v32, v28
	v_max_f32_e32 v28, 0xc2700000, v33
	v_add_f32_e32 v33, 1.0, v29
	v_rcp_f32_e32 v33, v33
	v_cmp_nle_f32_e32 vcc, 0, v25
	v_mul_f32_e32 v32, 0x3f317218, v32
	v_max_f32_e32 v39, 0xc2700000, v39
	v_cndmask_b32_e32 v25, 1.0, v29, vcc
	v_mul_f32_e64 v29, |v30|, s20
	v_exp_f32_e32 v29, v29
	v_mul_f32_e32 v25, v25, v33
	v_fma_f32 v25, v25, v78, v65
	v_log_f32_e32 v33, v25
	v_max_f32_e32 v25, 0xc2700000, v32
	v_add_f32_e32 v32, 1.0, v29
	v_rcp_f32_e32 v32, v32
	v_cmp_nle_f32_e32 vcc, 0, v30
	v_mul_f32_e64 v30, |v26|, s20
	v_exp_f32_e32 v30, v30
	v_cndmask_b32_e32 v29, 1.0, v29, vcc
	v_mul_f32_e32 v29, v29, v32
	v_mul_f32_e32 v33, 0x3f317218, v33
	v_fma_f32 v29, v29, v57, v70
	v_log_f32_e32 v32, v29
	v_max_f32_e32 v29, 0xc2700000, v33
	v_add_f32_e32 v33, 1.0, v30
	v_rcp_f32_e32 v33, v33
	v_cmp_nle_f32_e32 vcc, 0, v26
	v_mul_f32_e32 v32, 0x3f317218, v32
	global_store_dwordx4 v[40:41], v[36:39], off offset:16
	v_cndmask_b32_e32 v26, 1.0, v30, vcc
	v_mul_f32_e64 v30, |v31|, s20
	v_exp_f32_e32 v30, v30
	v_mul_f32_e32 v26, v26, v33
	v_fma_f32 v26, v26, v62, v66
	v_log_f32_e32 v33, v26
	v_max_f32_e32 v26, 0xc2700000, v32
	v_add_f32_e32 v32, 1.0, v30
	v_rcp_f32_e32 v32, v32
	v_cmp_nle_f32_e32 vcc, 0, v31
	v_mul_f32_e64 v31, |v27|, s20
	v_exp_f32_e32 v31, v31
	v_cndmask_b32_e32 v30, 1.0, v30, vcc
	v_mul_f32_e32 v30, v30, v32
	v_mul_f32_e32 v33, 0x3f317218, v33
	v_fma_f32 v30, v30, v58, v71
	v_log_f32_e32 v32, v30
	v_max_f32_e32 v30, 0xc2700000, v33
	v_add_f32_e32 v33, 1.0, v31
	v_rcp_f32_e32 v33, v33
	v_cmp_nle_f32_e32 vcc, 0, v27
	v_mul_f32_e32 v32, 0x3f317218, v32
	s_nop 0
	v_cndmask_b32_e32 v27, 1.0, v31, vcc
	v_mul_f32_e32 v27, v27, v33
	v_fma_f32 v27, v27, v59, v67
	v_log_f32_e32 v31, v27
	v_max_f32_e32 v27, 0xc2700000, v32
	v_mul_f32_e64 v32, |v16|, s20
	v_exp_f32_e32 v34, v32
	v_lshl_add_u64 v[32:33], v[88:89], 0, v[76:77]
	global_store_dwordx4 v[32:33], v[24:27], off
	v_cmp_nle_f32_e32 vcc, 0, v16
	v_add_f32_e32 v35, 1.0, v34
	v_mul_f32_e64 v24, |v8|, s20
	v_rcp_f32_e32 v35, v35
	v_exp_f32_e32 v24, v24
	v_cndmask_b32_e32 v16, 1.0, v34, vcc
	v_cmp_nle_f32_e32 vcc, 0, v8
	v_mul_f32_e32 v16, v16, v35
	v_add_f32_e32 v25, 1.0, v24
	v_fma_f32 v16, v16, v60, v68
	v_rcp_f32_e32 v25, v25
	v_log_f32_e32 v16, v16
	v_cndmask_b32_e32 v8, 1.0, v24, vcc
	v_mul_f32_e64 v24, |v17|, s20
	v_exp_f32_e32 v24, v24
	v_mul_f32_e32 v8, v8, v25
	v_mul_f32_e32 v16, 0x3f317218, v16
	v_fma_f32 v8, v8, v56, v64
	v_log_f32_e32 v25, v8
	v_max_f32_e32 v8, 0xc2700000, v16
	v_add_f32_e32 v16, 1.0, v24
	v_rcp_f32_e32 v16, v16
	v_cmp_nle_f32_e32 vcc, 0, v17
	v_mul_f32_e32 v25, 0x3f317218, v25
	v_mul_f32_e32 v31, 0x3f317218, v31
	v_cndmask_b32_e32 v17, 1.0, v24, vcc
	v_mul_f32_e32 v16, v17, v16
	v_mul_f32_e64 v17, |v9|, s20
	v_exp_f32_e32 v17, v17
	v_fma_f32 v16, v16, v61, v69
	v_log_f32_e32 v24, v16
	v_max_f32_e32 v16, 0xc2700000, v25
	v_add_f32_e32 v25, 1.0, v17
	v_rcp_f32_e32 v25, v25
	v_cmp_nle_f32_e32 vcc, 0, v9
	v_mul_f32_e32 v24, 0x3f317218, v24
	v_max_f32_e32 v31, 0xc2700000, v31
	v_cndmask_b32_e32 v9, 1.0, v17, vcc
	v_mul_f32_e64 v17, |v18|, s20
	v_exp_f32_e32 v17, v17
	v_mul_f32_e32 v9, v9, v25
	v_fma_f32 v9, v9, v78, v65
	v_log_f32_e32 v25, v9
	v_max_f32_e32 v9, 0xc2700000, v24
	v_add_f32_e32 v24, 1.0, v17
	v_rcp_f32_e32 v24, v24
	v_cmp_nle_f32_e32 vcc, 0, v18
	v_mul_f32_e64 v18, |v10|, s20
	v_exp_f32_e32 v18, v18
	v_cndmask_b32_e32 v17, 1.0, v17, vcc
	v_mul_f32_e32 v17, v17, v24
	v_mul_f32_e32 v25, 0x3f317218, v25
	v_fma_f32 v17, v17, v57, v70
	v_log_f32_e32 v24, v17
	v_max_f32_e32 v17, 0xc2700000, v25
	v_add_f32_e32 v25, 1.0, v18
	v_rcp_f32_e32 v25, v25
	v_cmp_nle_f32_e32 vcc, 0, v10
	v_mul_f32_e32 v24, 0x3f317218, v24
	global_store_dwordx4 v[32:33], v[28:31], off offset:16
	v_cndmask_b32_e32 v10, 1.0, v18, vcc
	v_mul_f32_e64 v18, |v19|, s20
	v_exp_f32_e32 v18, v18
	v_mul_f32_e32 v10, v10, v25
	v_fma_f32 v10, v10, v62, v66
	v_log_f32_e32 v25, v10
	v_max_f32_e32 v10, 0xc2700000, v24
	v_add_f32_e32 v24, 1.0, v18
	v_rcp_f32_e32 v24, v24
	v_cmp_nle_f32_e32 vcc, 0, v19
	v_mul_f32_e64 v19, |v11|, s20
	v_exp_f32_e32 v19, v19
	v_cndmask_b32_e32 v18, 1.0, v18, vcc
	v_mul_f32_e32 v18, v18, v24
	v_mul_f32_e32 v25, 0x3f317218, v25
	v_fma_f32 v18, v18, v58, v71
	v_log_f32_e32 v24, v18
	v_max_f32_e32 v18, 0xc2700000, v25
	v_add_f32_e32 v25, 1.0, v19
	v_rcp_f32_e32 v25, v25
	v_cmp_nle_f32_e32 vcc, 0, v11
	v_mul_f32_e32 v24, 0x3f317218, v24
	s_nop 0
	v_cndmask_b32_e32 v11, 1.0, v19, vcc
	v_mul_f32_e32 v11, v11, v25
	v_fma_f32 v11, v11, v59, v67
	v_log_f32_e32 v19, v11
	v_max_f32_e32 v11, 0xc2700000, v24
	v_mul_f32_e64 v24, |v0|, s20
	v_exp_f32_e32 v26, v24
	v_lshl_add_u64 v[24:25], v[80:81], 0, v[76:77]
	global_store_dwordx4 v[24:25], v[8:11], off
	v_cmp_nle_f32_e32 vcc, 0, v0
	v_add_f32_e32 v27, 1.0, v26
	v_mul_f32_e64 v8, |v4|, s20
	v_exp_f32_e32 v8, v8
	v_cndmask_b32_e32 v0, 1.0, v26, vcc
	v_cmp_nle_f32_e32 vcc, 0, v4
	v_rcp_f32_e32 v27, v27
	v_add_f32_e32 v9, 1.0, v8
	v_cndmask_b32_e32 v4, 1.0, v8, vcc
	v_mul_f32_e64 v8, |v1|, s20
	v_rcp_f32_e32 v9, v9
	v_exp_f32_e32 v8, v8
	v_cmp_nle_f32_e32 vcc, 0, v1
	v_mul_f32_e32 v0, v0, v27
	v_mul_f32_e32 v4, v4, v9
	v_add_f32_e32 v9, 1.0, v8
	v_cndmask_b32_e32 v1, 1.0, v8, vcc
	v_mul_f32_e64 v8, |v5|, s20
	v_rcp_f32_e32 v9, v9
	v_exp_f32_e32 v8, v8
	v_cmp_nle_f32_e32 vcc, 0, v5
	v_fma_f32 v0, v0, v60, v68
	v_mul_f32_e32 v1, v1, v9
	v_add_f32_e32 v9, 1.0, v8
	v_cndmask_b32_e32 v5, 1.0, v8, vcc
	v_mul_f32_e64 v8, |v2|, s20
	v_rcp_f32_e32 v9, v9
	v_exp_f32_e32 v8, v8
	v_cmp_nle_f32_e32 vcc, 0, v2
	v_fma_f32 v1, v1, v61, v69
	v_mul_f32_e32 v5, v5, v9
	v_add_f32_e32 v9, 1.0, v8
	v_cndmask_b32_e32 v2, 1.0, v8, vcc
	v_mul_f32_e64 v8, |v6|, s20
	v_rcp_f32_e32 v9, v9
	v_exp_f32_e32 v8, v8
	v_cmp_nle_f32_e32 vcc, 0, v6
	v_log_f32_e32 v0, v0
	v_mul_f32_e32 v2, v2, v9
	v_add_f32_e32 v9, 1.0, v8
	v_cndmask_b32_e32 v6, 1.0, v8, vcc
	v_mul_f32_e64 v8, |v3|, s20
	v_rcp_f32_e32 v9, v9
	v_exp_f32_e32 v8, v8
	v_cmp_nle_f32_e32 vcc, 0, v3
	v_fma_f32 v2, v2, v57, v70
	v_mul_f32_e32 v6, v6, v9
	v_add_f32_e32 v9, 1.0, v8
	v_rcp_f32_e32 v9, v9
	v_cndmask_b32_e32 v3, 1.0, v8, vcc
	v_mul_f32_e64 v8, |v7|, s20
	v_exp_f32_e32 v8, v8
	v_mul_f32_e32 v3, v3, v9
	v_fma_f32 v3, v3, v58, v71
	v_log_f32_e32 v1, v1
	v_log_f32_e32 v2, v2
	v_log_f32_e32 v3, v3
	v_add_f32_e32 v9, 1.0, v8
	v_rcp_f32_e32 v9, v9
	v_cmp_nle_f32_e32 vcc, 0, v7
	v_mul_f32_e32 v0, 0x3f317218, v0
	v_mul_f32_e32 v1, 0x3f317218, v1
	v_mul_f32_e32 v2, 0x3f317218, v2
	v_mul_f32_e32 v3, 0x3f317218, v3
	v_cndmask_b32_e32 v7, 1.0, v8, vcc
	v_mul_f32_e64 v8, |v20|, s20
	v_max_f32_e32 v0, 0xc2700000, v0
	v_max_f32_e32 v1, 0xc2700000, v1
	v_max_f32_e32 v2, 0xc2700000, v2
	v_mul_f32_e32 v7, v7, v9
	v_max_f32_e32 v3, 0xc2700000, v3
	v_exp_f32_e32 v10, v8
	v_lshl_add_u64 v[8:9], v[74:75], 0, v[76:77]
	global_store_dwordx4 v[8:9], v[0:3], off
	v_cmp_nle_f32_e32 vcc, 0, v20
	v_fma_f32 v4, v4, v56, v64
	v_mul_f32_e64 v1, |v12|, s20
	v_exp_f32_e32 v1, v1
	v_cndmask_b32_e32 v0, 1.0, v10, vcc
	v_cmp_nle_f32_e32 vcc, 0, v12
	v_fma_f32 v5, v5, v78, v65
	v_add_f32_e32 v2, 1.0, v1
	v_rcp_f32_e32 v2, v2
	v_cndmask_b32_e32 v1, 1.0, v1, vcc
	v_cmp_nle_f32_e32 vcc, 0, v21
	v_fma_f32 v6, v6, v62, v66
	v_mul_f32_e32 v1, v1, v2
	v_mul_f32_e64 v2, |v21|, s20
	v_exp_f32_e32 v2, v2
	v_fma_f32 v1, v1, v56, v64
	v_log_f32_e32 v1, v1
	v_fma_f32 v7, v7, v59, v67
	v_add_f32_e32 v3, 1.0, v2
	v_rcp_f32_e32 v3, v3
	v_cndmask_b32_e32 v2, 1.0, v2, vcc
	v_mul_f32_e32 v1, 0x3f317218, v1
	v_max_f32_e32 v12, 0xc2700000, v1
	v_mul_f32_e32 v2, v2, v3
	v_mul_f32_e64 v3, |v13|, s20
	v_exp_f32_e32 v3, v3
	v_log_f32_e32 v4, v4
	v_log_f32_e32 v5, v5
	v_log_f32_e32 v6, v6
	v_add_f32_e32 v1, 1.0, v3
	v_rcp_f32_e32 v1, v1
	v_log_f32_e32 v7, v7
	v_cmp_nle_f32_e32 vcc, 0, v13
	v_fma_f32 v2, v2, v61, v69
	v_mul_f32_e32 v4, 0x3f317218, v4
	v_cndmask_b32_e32 v3, 1.0, v3, vcc
	v_mul_f32_e32 v1, v3, v1
	v_mul_f32_e32 v5, 0x3f317218, v5
	v_mul_f32_e32 v6, 0x3f317218, v6
	v_mul_f32_e32 v7, 0x3f317218, v7
	v_log_f32_e32 v2, v2
	v_fma_f32 v1, v1, v78, v65
	v_max_f32_e32 v4, 0xc2700000, v4
	v_max_f32_e32 v5, 0xc2700000, v5
	v_max_f32_e32 v6, 0xc2700000, v6
	v_max_f32_e32 v7, 0xc2700000, v7
	v_log_f32_e32 v3, v1
	v_mul_f32_e64 v1, |v22|, s20
	global_store_dwordx4 v[8:9], v[4:7], off offset:16
	v_mul_f32_e32 v2, 0x3f317218, v2
	v_cmp_nle_f32_e32 vcc, 0, v22
	v_exp_f32_e32 v4, v1
	v_max_f32_e32 v1, 0xc2700000, v2
	v_mul_f32_e32 v2, 0x3f317218, v3
	v_max_f32_e32 v13, 0xc2700000, v2
	v_add_f32_e32 v2, 1.0, v4
	v_mul_f32_e64 v3, |v14|, s20
	v_rcp_f32_e32 v2, v2
	v_exp_f32_e32 v3, v3
	v_cndmask_b32_e32 v4, 1.0, v4, vcc
	v_cmp_nle_f32_e32 vcc, 0, v14
	v_mul_f32_e32 v2, v4, v2
	v_add_f32_e32 v4, 1.0, v3
	v_rcp_f32_e32 v4, v4
	v_cndmask_b32_e32 v3, 1.0, v3, vcc
	v_mul_f32_e64 v6, |v15|, s20
	v_exp_f32_e32 v6, v6
	v_mul_f32_e32 v3, v3, v4
	v_mul_f32_e64 v4, |v23|, s20
	v_exp_f32_e32 v4, v4
	v_cmp_nle_f32_e32 vcc, 0, v23
	v_add_f32_e32 v11, 1.0, v10
	v_rcp_f32_e32 v11, v11
	v_add_f32_e32 v5, 1.0, v4
	v_rcp_f32_e32 v5, v5
	v_cndmask_b32_e32 v4, 1.0, v4, vcc
	v_cmp_nle_f32_e32 vcc, 0, v15
	v_mul_f32_e32 v0, v0, v11
	v_mul_f32_e32 v4, v4, v5
	v_fmac_f32_e32 v71, v4, v58
	v_add_f32_e32 v4, 1.0, v6
	v_rcp_f32_e32 v4, v4
	v_cndmask_b32_e32 v6, 1.0, v6, vcc
	v_fma_f32 v3, v3, v62, v66
	v_fma_f32 v0, v0, v60, v68
	v_mul_f32_e32 v4, v6, v4
	v_fma_f32 v2, v2, v57, v70
	v_log_f32_e32 v3, v3
	v_fmac_f32_e32 v67, v4, v59
	v_log_f32_e32 v0, v0
	v_log_f32_e32 v2, v2
	v_log_f32_e32 v5, v71
	v_log_f32_e32 v4, v67
	v_mul_f32_e32 v3, 0x3f317218, v3
	v_mul_f32_e32 v19, 0x3f317218, v19
	v_mul_f32_e32 v0, 0x3f317218, v0
	v_mul_f32_e32 v2, 0x3f317218, v2
	v_max_f32_e32 v14, 0xc2700000, v3
	v_mul_f32_e32 v3, 0x3f317218, v5
	v_mul_f32_e32 v4, 0x3f317218, v4
	v_max_f32_e32 v19, 0xc2700000, v19
	v_max_f32_e32 v0, 0xc2700000, v0
	v_max_f32_e32 v2, 0xc2700000, v2
	v_max_f32_e32 v3, 0xc2700000, v3
	v_max_f32_e32 v15, 0xc2700000, v4
	global_store_dwordx4 v[24:25], v[16:19], off offset:16
	global_store_dwordx4 v[116:117], v[0:3], off
	s_branch .LBB0_861

.LBB0_1393:
	v_lshl_or_b32 v160, s73, 6, v169
	v_mov_b32_e32 v203, v167
	v_lshl_add_u32 v132, v160, 3, s67
	ds_read_b64 v[132:133], v132
	v_cmp_gt_u32_e64 s[46:47], 2, v169
	s_waitcnt lgkmcnt(0)
	v_pk_mul_f32 v[152:153], v[132:133], s[96:97] op_sel_hi:[1,0]
	v_fma_f32 v132, -v152, v152, v153
	v_max_f32_e32 v132, 0, v132
	v_add_f32_e32 v132, 0x3727c5ac, v132
	v_rsq_f32_e32 v180, v132
	ds_read_b128 v[222:225], v203 offset:2048
	ds_read_b128 v[226:229], v203 offset:2560
	ds_read_b128 v[230:233], v203 offset:2064
	ds_read_b128 v[234:237], v203 offset:2576
	v_mul_f32_e64 v188, v180, -v152
	ds_read_b128 v[238:241], v203 offset:3072
	ds_read_b128 v[244:247], v203 offset:3584
	s_waitcnt lgkmcnt(0)
	v_pk_fma_f32 v[132:133], v[222:223], v[188:189], v[226:227] op_sel_hi:[1,0,1]
	v_pk_fma_f32 v[134:135], v[224:225], v[188:189], v[228:229] op_sel_hi:[1,0,1]
	v_pk_fma_f32 v[136:137], v[230:231], v[188:189], v[234:235] op_sel_hi:[1,0,1]
	v_pk_fma_f32 v[138:139], v[232:233], v[188:189], v[236:237] op_sel_hi:[1,0,1]
	ds_read_b128 v[144:147], v203 offset:3088
	ds_read_b128 v[184:187], v203 offset:3600
	v_pk_fma_f32 v[132:133], v[124:125], v[180:181], v[132:133] op_sel_hi:[1,0,1]
	v_pk_fma_f32 v[134:135], v[126:127], v[180:181], v[134:135] op_sel_hi:[1,0,1]
	v_pk_fma_f32 v[136:137], v[120:121], v[180:181], v[136:137] op_sel_hi:[1,0,1]
	v_pk_fma_f32 v[138:139], v[122:123], v[180:181], v[138:139] op_sel_hi:[1,0,1]
	v_pk_fma_f32 v[148:149], v[238:239], v[188:189], v[244:245] op_sel_hi:[1,0,1]
	v_pk_fma_f32 v[150:151], v[240:241], v[188:189], v[246:247] op_sel_hi:[1,0,1]
	s_waitcnt lgkmcnt(0)
	v_pk_fma_f32 v[144:145], v[144:145], v[188:189], v[184:185] op_sel_hi:[1,0,1]
	v_pk_fma_f32 v[146:147], v[146:147], v[188:189], v[186:187] op_sel_hi:[1,0,1]
	s_and_b64 s[4:5], s[4:5], s[46:47]
	v_cmp_eq_u32_e64 s[42:43], 0, v169
	v_cmp_lt_u32_e32 vcc, 1, v169
	v_cmp_eq_u32_e64 s[44:45], 1, v169
	v_ashrrev_i32_e32 v175, 31, v174
	v_pk_fma_f32 v[150:151], v[94:95], v[180:181], v[150:151] op_sel_hi:[1,0,1]
	v_pk_fma_f32 v[144:145], v[88:89], v[180:181], v[144:145] op_sel_hi:[1,0,1]
	v_pk_fma_f32 v[146:147], v[90:91], v[180:181], v[146:147] op_sel_hi:[1,0,1]
	v_mov_b32_dpp v173, v132 row_ror:1 row_mask:0xf bank_mask:0xf
	v_mov_b32_dpp v185, v133 row_ror:1 row_mask:0xf bank_mask:0xf
	v_mov_b32_dpp v184, v132 row_ror:2 row_mask:0xf bank_mask:0xf
	v_mov_b32_dpp v186, v133 row_ror:2 row_mask:0xf bank_mask:0xf
	v_mov_b32_dpp v187, v134 row_ror:1 row_mask:0xf bank_mask:0xf
	v_mov_b32_dpp v194, v135 row_ror:1 row_mask:0xf bank_mask:0xf
	v_mov_b32_dpp v188, v134 row_ror:2 row_mask:0xf bank_mask:0xf
	v_mov_b32_dpp v189, v135 row_ror:2 row_mask:0xf bank_mask:0xf
	v_mov_b32_dpp v195, v136 row_ror:1 row_mask:0xf bank_mask:0xf
	v_mov_b32_dpp v197, v137 row_ror:1 row_mask:0xf bank_mask:0xf
	v_mov_b32_dpp v196, v136 row_ror:2 row_mask:0xf bank_mask:0xf
	v_mov_b32_dpp v198, v137 row_ror:2 row_mask:0xf bank_mask:0xf
	v_mov_b32_dpp v201, v138 row_ror:1 row_mask:0xf bank_mask:0xf
	v_mov_b32_dpp v202, v139 row_ror:1 row_mask:0xf bank_mask:0xf
	v_mov_b32_dpp v199, v138 row_ror:2 row_mask:0xf bank_mask:0xf
	v_mov_b32_dpp v200, v139 row_ror:2 row_mask:0xf bank_mask:0xf
	v_pk_fma_f32 v[148:149], v[92:93], v[180:181], v[148:149] op_sel_hi:[1,0,1]
	s_xor_b64 s[8:9], s[4:5], -1
	s_and_saveexec_b64 s[4:5], s[8:9]
	s_cbranch_execz .LBB0_1395
	ds_read_b128 v[178:181], v203 offset:1040
	ds_read_b128 v[204:207], v203 offset:528
	ds_read_b128 v[152:155], v203
	ds_read_b128 v[208:211], v203 offset:16
	ds_read_b128 v[212:215], v203 offset:1552
	v_cndmask_b32_e64 v158, v158, v164, s[44:45]
	v_cndmask_b32_e64 v159, v159, v165, s[44:45]
	v_cndmask_b32_e32 v159, v159, v200, vcc
	v_cndmask_b32_e32 v158, v158, v199, vcc
	v_cndmask_b32_e64 v177, v202, v165, s[42:43]
	v_cndmask_b32_e64 v176, v201, v164, s[42:43]
	s_waitcnt lgkmcnt(0)
	v_pk_fma_f32 v[158:159], v[158:159], v[210:211], v[214:215]
	v_cndmask_b32_e64 v156, v156, v162, s[44:45]
	v_pk_fma_f32 v[158:159], v[176:177], v[206:207], v[158:159]
	v_cndmask_b32_e64 v157, v157, v163, s[44:45]
	v_pk_fma_f32 v[158:159], v[138:139], v[180:181], v[158:159]
	v_cndmask_b32_e32 v157, v157, v198, vcc
	v_pk_mul_f32 v[164:165], v[146:147], v[158:159]
	v_pk_mul_f32 v[158:159], v[158:159], s[20:21] op_sel_hi:[1,0]
	v_cndmask_b32_e32 v156, v156, v196, vcc
	v_exp_f32_e32 v158, v158
	v_exp_f32_e32 v159, v159
	v_pk_fma_f32 v[156:157], v[156:157], v[208:209], v[212:213]
	v_cndmask_b32_e64 v130, v130, v142, s[44:45]
	v_cndmask_b32_e64 v131, v131, v143, s[44:45]
	v_pk_add_f32 v[158:159], v[158:159], 1.0 op_sel_hi:[1,0]
	v_cndmask_b32_e32 v131, v131, v189, vcc
	v_rcp_f32_e32 v158, v158
	v_rcp_f32_e32 v159, v159
	v_cndmask_b32_e32 v130, v130, v188, vcc
	v_cndmask_b32_e64 v181, v194, v143, s[42:43]
	v_cndmask_b32_e64 v180, v187, v142, s[42:43]
	v_pk_mul_f32 v[176:177], v[164:165], v[158:159]
	v_cndmask_b32_e64 v159, v197, v163, s[42:43]
	v_cndmask_b32_e64 v158, v195, v162, s[42:43]
	v_pk_fma_f32 v[156:157], v[158:159], v[204:205], v[156:157]
	ds_read_b128 v[204:207], v203 offset:1536
	v_pk_fma_f32 v[156:157], v[136:137], v[178:179], v[156:157]
	ds_read_b128 v[162:165], v203 offset:512
	v_pk_mul_f32 v[158:159], v[144:145], v[156:157]
	v_pk_mul_f32 v[156:157], v[156:157], s[20:21] op_sel_hi:[1,0]
	s_waitcnt lgkmcnt(0)
	v_pk_fma_f32 v[130:131], v[130:131], v[154:155], v[206:207]
	v_exp_f32_e32 v156, v156
	v_exp_f32_e32 v157, v157
	v_pk_fma_f32 v[130:131], v[180:181], v[164:165], v[130:131]
	v_cndmask_b32_e64 v128, v128, v140, s[44:45]
	v_cndmask_b32_e64 v129, v129, v141, s[44:45]
	v_pk_add_f32 v[156:157], v[156:157], 1.0 op_sel_hi:[1,0]
	v_cndmask_b32_e32 v129, v129, v186, vcc
	v_rcp_f32_e32 v156, v156
	v_rcp_f32_e32 v157, v157
	v_cndmask_b32_e32 v128, v128, v184, vcc
	v_pk_fma_f32 v[128:129], v[128:129], v[152:153], v[204:205]
	s_movk_i32 s8, 0x1600
	v_pk_mul_f32 v[178:179], v[158:159], v[156:157]
	ds_read_b128 v[156:159], v203 offset:1024
	s_waitcnt lgkmcnt(0)
	v_pk_fma_f32 v[130:131], v[134:135], v[158:159], v[130:131]
	s_nop 0
	v_pk_mul_f32 v[142:143], v[150:151], v[130:131]
	v_pk_mul_f32 v[130:131], v[130:131], s[20:21] op_sel_hi:[1,0]
	s_nop 0
	v_exp_f32_e32 v130, v130
	v_exp_f32_e32 v131, v131
	s_nop 0
	v_pk_add_f32 v[130:131], v[130:131], 1.0 op_sel_hi:[1,0]
	s_nop 0
	v_rcp_f32_e32 v130, v130
	v_rcp_f32_e32 v131, v131
	s_nop 0
	v_pk_mul_f32 v[130:131], v[142:143], v[130:131]
	v_cndmask_b32_e64 v143, v185, v141, s[42:43]
	v_cndmask_b32_e64 v142, v173, v140, s[42:43]
	v_pk_fma_f32 v[128:129], v[142:143], v[162:163], v[128:129]
	v_lshl_add_u32 v142, s56, 8, v160
	v_pk_fma_f32 v[128:129], v[132:133], v[156:157], v[128:129]
	s_nop 0
	v_pk_mul_f32 v[140:141], v[148:149], v[128:129]
	v_pk_mul_f32 v[128:129], v[128:129], s[20:21] op_sel_hi:[1,0]
	s_nop 0
	v_exp_f32_e32 v128, v128
	v_exp_f32_e32 v129, v129
	s_nop 0
	v_pk_add_f32 v[128:129], v[128:129], 1.0 op_sel_hi:[1,0]
	s_nop 0
	v_rcp_f32_e32 v128, v128
	v_rcp_f32_e32 v129, v129
	s_nop 0
	v_pk_mul_f32 v[128:129], v[140:141], v[128:129]
	v_mov_b64_e32 v[140:141], s[60:61]
	v_mad_i64_i32 v[140:141], s[8:9], v142, s8, v[140:141]
	v_cvt_pk_bf16_f32 v128, v128, v129
	v_cvt_pk_bf16_f32 v129, v130, v131
	v_cvt_pk_bf16_f32 v130, v178, v179
	v_cvt_pk_bf16_f32 v131, v176, v177
	v_lshl_add_u64 v[140:141], v[174:175], 1, v[140:141]
	global_store_dwordx4 v[140:141], v[128:131], off nt

.LBB0_1397:
	s_or_b64 exec, exec, s[4:5]
	v_or_b32_e32 v208, 16, v160
	v_mov_b32_e32 v209, v167
	v_lshl_add_u32 v128, v208, 3, s67
	ds_read_b64 v[136:137], v128
	s_waitcnt lgkmcnt(0)
	v_pk_mul_f32 v[136:137], v[136:137], s[96:97] op_sel_hi:[1,0]
	v_fma_f32 v137, -v136, v136, v137
	v_max_f32_e32 v137, 0, v137
	v_add_f32_e32 v137, 0x3727c5ac, v137
	v_rsq_f32_e32 v150, v137
	s_nop 0
	v_mul_f32_e64 v152, v150, -v136
	v_pk_fma_f32 v[128:129], v[222:223], v[152:153], v[226:227] op_sel_hi:[1,0,1]
	v_pk_fma_f32 v[130:131], v[224:225], v[152:153], v[228:229] op_sel_hi:[1,0,1]
	v_pk_fma_f32 v[136:137], v[116:117], v[150:151], v[128:129] op_sel_hi:[1,0,1]
	v_pk_fma_f32 v[128:129], v[230:231], v[152:153], v[234:235] op_sel_hi:[1,0,1]
	v_pk_fma_f32 v[140:141], v[118:119], v[150:151], v[130:131] op_sel_hi:[1,0,1]
	v_pk_fma_f32 v[180:181], v[112:113], v[150:151], v[128:129] op_sel_hi:[1,0,1]
	v_pk_fma_f32 v[138:139], v[232:233], v[152:153], v[236:237] op_sel_hi:[1,0,1]
	ds_read_b128 v[88:91], v209 offset:3088
	ds_read_b128 v[92:95], v209 offset:3600
	v_pk_fma_f32 v[190:191], v[114:115], v[150:151], v[138:139] op_sel_hi:[1,0,1]
	s_waitcnt lgkmcnt(0)
	v_pk_fma_f32 v[130:131], v[240:241], v[152:153], v[246:247] op_sel_hi:[1,0,1]
	v_pk_fma_f32 v[128:129], v[238:239], v[152:153], v[244:245] op_sel_hi:[1,0,1]
	v_pk_fma_f32 v[138:139], v[86:87], v[150:151], v[130:131] op_sel_hi:[1,0,1]
	v_pk_fma_f32 v[130:131], v[88:89], v[152:153], v[92:93] op_sel_hi:[1,0,1]
	v_pk_fma_f32 v[142:143], v[84:85], v[150:151], v[128:129] op_sel_hi:[1,0,1]
	v_pk_fma_f32 v[204:205], v[80:81], v[150:151], v[130:131] op_sel_hi:[1,0,1]
	v_pk_fma_f32 v[130:131], v[90:91], v[152:153], v[94:95] op_sel_hi:[1,0,1]
	ds_read_b128 v[120:123], v209 offset:1040
	v_pk_fma_f32 v[206:207], v[82:83], v[150:151], v[130:131] op_sel_hi:[1,0,1]
	ds_read_b128 v[124:127], v209 offset:16
	ds_read_b128 v[148:151], v209 offset:1552
	ds_read_b128 v[176:179], v209 offset:528
	ds_read_b128 v[128:131], v209
	v_mov_b32_dpp v210, v190 row_ror:1 row_mask:0xf bank_mask:0xf
	v_mov_b32_dpp v211, v191 row_ror:1 row_mask:0xf bank_mask:0xf
	v_mov_b32_dpp v212, v190 row_ror:2 row_mask:0xf bank_mask:0xf
	v_mov_b32_dpp v213, v191 row_ror:2 row_mask:0xf bank_mask:0xf
	v_cndmask_b32_e64 v203, v211, v202, s[42:43]
	v_cndmask_b32_e64 v202, v210, v201, s[42:43]
	v_cndmask_b32_e32 v201, v200, v213, vcc
	v_cndmask_b32_e32 v200, v199, v212, vcc
	v_mov_b32_dpp v163, v180 row_ror:2 row_mask:0xf bank_mask:0xf
	v_mov_b32_dpp v165, v181 row_ror:2 row_mask:0xf bank_mask:0xf
	s_waitcnt lgkmcnt(0)
	v_pk_fma_f32 v[146:147], v[200:201], v[126:127], v[150:151]
	v_mov_b32_dpp v162, v180 row_ror:1 row_mask:0xf bank_mask:0xf
	v_mov_b32_dpp v164, v181 row_ror:1 row_mask:0xf bank_mask:0xf
	v_pk_fma_f32 v[146:147], v[202:203], v[178:179], v[146:147]
	v_cndmask_b32_e32 v179, v198, v165, vcc
	v_cndmask_b32_e32 v178, v196, v163, vcc
	v_cndmask_b32_e64 v151, v164, v197, s[42:43]
	v_cndmask_b32_e64 v150, v162, v195, s[42:43]
	v_pk_fma_f32 v[144:145], v[178:179], v[124:125], v[148:149]
	v_pk_fma_f32 v[134:135], v[190:191], v[122:123], v[146:147]
	v_pk_fma_f32 v[144:145], v[150:151], v[176:177], v[144:145]
	v_pk_mul_f32 v[146:147], v[134:135], s[20:21] op_sel_hi:[1,0]
	v_pk_fma_f32 v[132:133], v[180:181], v[120:121], v[144:145]
	v_exp_f32_e32 v146, v146
	v_pk_mul_f32 v[144:145], v[132:133], s[20:21] op_sel_hi:[1,0]
	v_exp_f32_e32 v147, v147
	v_exp_f32_e32 v144, v144
	v_exp_f32_e32 v145, v145
	v_pk_mul_f32 v[134:135], v[206:207], v[134:135]
	v_pk_add_f32 v[146:147], v[146:147], 1.0 op_sel_hi:[1,0]
	v_pk_mul_f32 v[132:133], v[204:205], v[132:133]
	v_pk_add_f32 v[144:145], v[144:145], 1.0 op_sel_hi:[1,0]
	v_rcp_f32_e32 v146, v146
	v_rcp_f32_e32 v147, v147
	v_rcp_f32_e32 v148, v144
	v_rcp_f32_e32 v149, v145
	v_pk_mul_f32 v[144:145], v[134:135], v[146:147]
	v_pk_mul_f32 v[146:147], v[132:133], v[148:149]
	ds_read_b128 v[132:135], v209 offset:1024
	ds_read_b128 v[148:151], v209 offset:1536
	ds_read_b128 v[176:179], v209 offset:512
	v_mov_b32_dpp v157, v140 row_ror:2 row_mask:0xf bank_mask:0xf
	v_mov_b32_dpp v158, v141 row_ror:2 row_mask:0xf bank_mask:0xf
	v_mov_b32_dpp v156, v140 row_ror:1 row_mask:0xf bank_mask:0xf
	v_mov_b32_dpp v159, v141 row_ror:1 row_mask:0xf bank_mask:0xf
	v_cndmask_b32_e32 v189, v189, v158, vcc
	v_cndmask_b32_e32 v188, v188, v157, vcc
	v_mov_b32_dpp v153, v136 row_ror:2 row_mask:0xf bank_mask:0xf
	v_mov_b32_dpp v155, v137 row_ror:2 row_mask:0xf bank_mask:0xf
	v_cndmask_b32_e64 v181, v159, v194, s[42:43]
	v_cndmask_b32_e64 v180, v156, v187, s[42:43]
	s_waitcnt lgkmcnt(0)
	v_pk_fma_f32 v[130:131], v[188:189], v[130:131], v[150:151]
	v_mov_b32_dpp v152, v136 row_ror:1 row_mask:0xf bank_mask:0xf
	v_mov_b32_dpp v154, v137 row_ror:1 row_mask:0xf bank_mask:0xf
	v_pk_fma_f32 v[130:131], v[180:181], v[178:179], v[130:131]
	v_cndmask_b32_e32 v151, v186, v155, vcc
	v_cndmask_b32_e32 v150, v184, v153, vcc
	v_pk_fma_f32 v[130:131], v[140:141], v[134:135], v[130:131]
	v_cndmask_b32_e64 v141, v154, v185, s[42:43]
	v_cndmask_b32_e64 v140, v152, v173, s[42:43]
	v_pk_fma_f32 v[128:129], v[150:151], v[128:129], v[148:149]
	v_pk_mul_f32 v[134:135], v[130:131], s[20:21] op_sel_hi:[1,0]
	v_pk_fma_f32 v[128:129], v[140:141], v[176:177], v[128:129]
	v_exp_f32_e32 v134, v134
	v_pk_fma_f32 v[128:129], v[136:137], v[132:133], v[128:129]
	v_exp_f32_e32 v135, v135
	v_pk_mul_f32 v[132:133], v[128:129], s[20:21] op_sel_hi:[1,0]
	v_pk_mul_f32 v[128:129], v[142:143], v[128:129]
	v_exp_f32_e32 v132, v132
	v_exp_f32_e32 v133, v133
	v_pk_add_f32 v[134:135], v[134:135], 1.0 op_sel_hi:[1,0]
	s_lshl_b32 s4, s56, 8
	v_rcp_f32_e32 v134, v134
	v_pk_add_f32 v[132:133], v[132:133], 1.0 op_sel_hi:[1,0]
	v_rcp_f32_e32 v135, v135
	v_rcp_f32_e32 v132, v132
	v_rcp_f32_e32 v133, v133
	v_pk_mul_f32 v[130:131], v[138:139], v[130:131]
	v_mov_b64_e32 v[148:149], s[60:61]
	s_movk_i32 s19, 0x1600
	v_pk_mul_f32 v[128:129], v[128:129], v[132:133]
	v_add_u32_e32 v132, s4, v208
	v_pk_mul_f32 v[130:131], v[130:131], v[134:135]
	v_mad_i64_i32 v[132:133], s[8:9], v132, s19, v[148:149]
	v_lshlrev_b64 v[150:151], 1, v[174:175]
	v_cvt_pk_bf16_f32 v128, v128, v129
	v_cvt_pk_bf16_f32 v129, v130, v131
	v_cvt_pk_bf16_f32 v130, v146, v147
	v_cvt_pk_bf16_f32 v131, v144, v145
	v_lshl_add_u64 v[132:133], v[132:133], 0, v[150:151]
	v_or_b32_e32 v147, 32, v160
	global_store_dwordx4 v[132:133], v[128:131], off nt
	v_mov_b32_e32 v173, v167
	s_nop 0
	v_lshl_add_u32 v128, v147, 3, s67
	ds_read_b64 v[128:129], v128
	s_waitcnt lgkmcnt(0)
	v_pk_mul_f32 v[136:137], v[128:129], s[96:97] op_sel_hi:[1,0]
	v_fma_f32 v128, -v136, v136, v137
	v_max_f32_e32 v128, 0, v128
	v_add_f32_e32 v128, 0x3727c5ac, v128
	v_rsq_f32_e32 v180, v128
	s_nop 0
	v_mul_f32_e64 v146, v180, -v136
	s_waitcnt lgkmcnt(0)
	v_pk_fma_f32 v[128:129], v[222:223], v[146:147], v[226:227] op_sel_hi:[1,0,1]
	v_pk_fma_f32 v[132:133], v[108:109], v[180:181], v[128:129] op_sel_hi:[1,0,1]
	v_pk_fma_f32 v[128:129], v[224:225], v[146:147], v[228:229] op_sel_hi:[1,0,1]
	v_pk_fma_f32 v[134:135], v[232:233], v[146:147], v[236:237] op_sel_hi:[1,0,1]
	v_pk_fma_f32 v[136:137], v[110:111], v[180:181], v[128:129] op_sel_hi:[1,0,1]
	v_pk_fma_f32 v[128:129], v[230:231], v[146:147], v[234:235] op_sel_hi:[1,0,1]
	v_pk_fma_f32 v[190:191], v[106:107], v[180:181], v[134:135] op_sel_hi:[1,0,1]
	v_pk_fma_f32 v[188:189], v[104:105], v[180:181], v[128:129] op_sel_hi:[1,0,1]
	s_nop 0
	v_mov_b32_dpp v219, v190 row_ror:2 row_mask:0xf bank_mask:0xf
	v_mov_b32_dpp v220, v191 row_ror:2 row_mask:0xf bank_mask:0xf
	v_mov_b32_dpp v217, v190 row_ror:1 row_mask:0xf bank_mask:0xf
	s_waitcnt lgkmcnt(0)
	v_pk_fma_f32 v[130:131], v[240:241], v[146:147], v[246:247] op_sel_hi:[1,0,1]
	v_pk_fma_f32 v[128:129], v[238:239], v[146:147], v[244:245] op_sel_hi:[1,0,1]
	v_pk_fma_f32 v[134:135], v[78:79], v[180:181], v[130:131] op_sel_hi:[1,0,1]
	v_pk_fma_f32 v[130:131], v[88:89], v[146:147], v[92:93] op_sel_hi:[1,0,1]
	v_pk_fma_f32 v[138:139], v[76:77], v[180:181], v[128:129] op_sel_hi:[1,0,1]
	v_pk_fma_f32 v[198:199], v[72:73], v[180:181], v[130:131] op_sel_hi:[1,0,1]
	v_pk_fma_f32 v[130:131], v[90:91], v[146:147], v[94:95] op_sel_hi:[1,0,1]
	v_pk_fma_f32 v[200:201], v[74:75], v[180:181], v[130:131] op_sel_hi:[1,0,1]
	ds_read_b128 v[80:83], v173 offset:1552
	ds_read_b128 v[84:87], v173 offset:528
	ds_read_b128 v[112:115], v173 offset:0
	v_mov_b32_dpp v218, v191 row_ror:1 row_mask:0xf bank_mask:0xf
	v_cndmask_b32_e32 v203, v213, v220, vcc
	v_cndmask_b32_e32 v202, v212, v219, vcc
	v_mov_b32_dpp v214, v189 row_ror:1 row_mask:0xf bank_mask:0xf
	v_mov_b32_dpp v215, v188 row_ror:2 row_mask:0xf bank_mask:0xf
	v_mov_b32_dpp v216, v189 row_ror:2 row_mask:0xf bank_mask:0xf
	v_cndmask_b32_e64 v181, v218, v211, s[42:43]
	v_cndmask_b32_e64 v180, v217, v210, s[42:43]
	s_waitcnt lgkmcnt(0)
	v_pk_fma_f32 v[178:179], v[202:203], v[126:127], v[82:83]
	v_mov_b32_dpp v209, v188 row_ror:1 row_mask:0xf bank_mask:0xf
	v_pk_fma_f32 v[178:179], v[180:181], v[86:87], v[178:179]
	v_cndmask_b32_e64 v181, v214, v164, s[42:43]
	v_cndmask_b32_e32 v165, v165, v216, vcc
	v_cndmask_b32_e32 v164, v163, v215, vcc
	v_cndmask_b32_e64 v180, v209, v162, s[42:43]
	v_pk_fma_f32 v[162:163], v[164:165], v[124:125], v[80:81]
	v_pk_fma_f32 v[142:143], v[190:191], v[122:123], v[178:179]
	v_pk_fma_f32 v[162:163], v[180:181], v[84:85], v[162:163]
	v_pk_mul_f32 v[178:179], v[142:143], s[20:21] op_sel_hi:[1,0]
	v_pk_fma_f32 v[162:163], v[188:189], v[120:121], v[162:163]
	v_exp_f32_e32 v178, v178
	v_pk_mul_f32 v[140:141], v[162:163], s[20:21] op_sel_hi:[1,0]
	v_exp_f32_e32 v179, v179
	v_exp_f32_e32 v140, v140
	v_exp_f32_e32 v141, v141
	v_pk_add_f32 v[164:165], v[178:179], 1.0 op_sel_hi:[1,0]
	v_pk_add_f32 v[140:141], v[140:141], 1.0 op_sel_hi:[1,0]
	v_rcp_f32_e32 v164, v164
	v_rcp_f32_e32 v165, v165
	v_rcp_f32_e32 v176, v140
	v_rcp_f32_e32 v177, v141
	v_pk_mul_f32 v[140:141], v[200:201], v[142:143]
	v_pk_mul_f32 v[142:143], v[198:199], v[162:163]
	v_pk_mul_f32 v[140:141], v[140:141], v[164:165]
	v_pk_mul_f32 v[142:143], v[142:143], v[176:177]
	ds_read_b128 v[116:119], v173 offset:1024
	ds_read_b128 v[176:179], v173 offset:1536
	ds_read_b128 v[184:187], v173 offset:512
	v_mov_b32_dpp v146, v133 row_ror:1 row_mask:0xf bank_mask:0xf
	v_mov_b32_dpp v145, v132 row_ror:2 row_mask:0xf bank_mask:0xf
	v_mov_b32_dpp v204, v133 row_ror:2 row_mask:0xf bank_mask:0xf
	v_mov_b32_dpp v206, v137 row_ror:1 row_mask:0xf bank_mask:0xf
	v_mov_b32_dpp v207, v136 row_ror:2 row_mask:0xf bank_mask:0xf
	v_mov_b32_dpp v208, v137 row_ror:2 row_mask:0xf bank_mask:0xf
	v_mov_b32_dpp v144, v132 row_ror:1 row_mask:0xf bank_mask:0xf
	v_mov_b32_dpp v205, v136 row_ror:1 row_mask:0xf bank_mask:0xf
	v_cndmask_b32_e64 v181, v206, v159, s[42:43]
	v_cndmask_b32_e32 v159, v158, v208, vcc
	v_cndmask_b32_e32 v158, v157, v207, vcc
	v_cndmask_b32_e64 v157, v146, v154, s[42:43]
	v_cndmask_b32_e32 v155, v155, v204, vcc
	v_cndmask_b32_e32 v154, v153, v145, vcc
	v_cndmask_b32_e64 v180, v205, v156, s[42:43]
	v_cndmask_b32_e64 v156, v144, v152, s[42:43]
	s_waitcnt lgkmcnt(0)
	v_pk_fma_f32 v[128:129], v[154:155], v[112:113], v[176:177]
	v_pk_fma_f32 v[130:131], v[158:159], v[114:115], v[178:179]
	v_pk_fma_f32 v[128:129], v[156:157], v[184:185], v[128:129]
	v_pk_fma_f32 v[130:131], v[180:181], v[186:187], v[130:131]
	v_pk_fma_f32 v[128:129], v[132:133], v[116:117], v[128:129]
	v_pk_fma_f32 v[130:131], v[136:137], v[118:119], v[130:131]
	v_pk_mul_f32 v[132:133], v[128:129], s[20:21] op_sel_hi:[1,0]
	v_pk_mul_f32 v[136:137], v[130:131], s[20:21] op_sel_hi:[1,0]
	v_exp_f32_e32 v132, v132
	v_exp_f32_e32 v133, v133
	v_exp_f32_e32 v136, v136
	v_exp_f32_e32 v137, v137
	v_pk_mul_f32 v[128:129], v[138:139], v[128:129]
	v_pk_add_f32 v[132:133], v[132:133], 1.0 op_sel_hi:[1,0]
	v_pk_mul_f32 v[130:131], v[134:135], v[130:131]
	v_pk_add_f32 v[136:137], v[136:137], 1.0 op_sel_hi:[1,0]
	v_rcp_f32_e32 v132, v132
	v_rcp_f32_e32 v133, v133
	v_rcp_f32_e32 v136, v136
	v_rcp_f32_e32 v137, v137
	v_or_b32_e32 v173, 48, v160
	v_pk_mul_f32 v[128:129], v[128:129], v[132:133]
	v_add_u32_e32 v132, s4, v147
	v_pk_mul_f32 v[130:131], v[130:131], v[136:137]
	v_mad_i64_i32 v[132:133], s[8:9], v132, s19, v[148:149]
	v_cvt_pk_bf16_f32 v128, v128, v129
	v_cvt_pk_bf16_f32 v129, v130, v131
	v_cvt_pk_bf16_f32 v130, v142, v143
	v_cvt_pk_bf16_f32 v131, v140, v141
	v_lshl_add_u64 v[132:133], v[132:133], 0, v[150:151]
	global_store_dwordx4 v[132:133], v[128:131], off nt
	v_mov_b32_e32 v147, v167
	s_nop 0
	v_lshl_add_u32 v128, v173, 3, s67
	ds_read_b64 v[128:129], v128
	s_waitcnt lgkmcnt(0)
	v_pk_mul_f32 v[142:143], v[128:129], s[96:97] op_sel_hi:[1,0]
	v_fma_f32 v128, -v142, v142, v143
	v_max_f32_e32 v128, 0, v128
	v_add_f32_e32 v128, 0x3727c5ac, v128
	v_rsq_f32_e32 v156, v128
	s_nop 0
	v_mul_f32_e64 v142, v156, -v142
	v_pk_fma_f32 v[130:131], v[222:223], v[142:143], v[226:227] op_sel_hi:[1,0,1]
	v_pk_fma_f32 v[158:159], v[232:233], v[142:143], v[236:237] op_sel_hi:[1,0,1]
	v_pk_fma_f32 v[162:163], v[100:101], v[156:157], v[130:131] op_sel_hi:[1,0,1]
	v_pk_fma_f32 v[130:131], v[224:225], v[142:143], v[228:229] op_sel_hi:[1,0,1]
	v_pk_fma_f32 v[178:179], v[98:99], v[156:157], v[158:159] op_sel_hi:[1,0,1]
	v_pk_fma_f32 v[164:165], v[102:103], v[156:157], v[130:131] op_sel_hi:[1,0,1]
	v_pk_fma_f32 v[130:131], v[230:231], v[142:143], v[234:235] op_sel_hi:[1,0,1]
	v_mov_b32_dpp v190, v178 row_ror:2 row_mask:0xf bank_mask:0xf
	v_pk_fma_f32 v[176:177], v[96:97], v[156:157], v[130:131] op_sel_hi:[1,0,1]
	v_mov_b32_dpp v191, v179 row_ror:2 row_mask:0xf bank_mask:0xf
	v_cndmask_b32_e32 v191, v220, v191, vcc
	v_cndmask_b32_e32 v190, v219, v190, vcc
	s_waitcnt lgkmcnt(0)
	v_pk_fma_f32 v[132:133], v[240:241], v[142:143], v[246:247] op_sel_hi:[1,0,1]
	v_pk_fma_f32 v[130:131], v[238:239], v[142:143], v[244:245] op_sel_hi:[1,0,1]
	v_pk_fma_f32 v[180:181], v[70:71], v[156:157], v[132:133] op_sel_hi:[1,0,1]
	v_pk_fma_f32 v[132:133], v[88:89], v[142:143], v[92:93] op_sel_hi:[1,0,1]
	v_pk_fma_f32 v[184:185], v[64:65], v[156:157], v[132:133] op_sel_hi:[1,0,1]
	v_pk_fma_f32 v[132:133], v[90:91], v[142:143], v[94:95] op_sel_hi:[1,0,1]
	v_mov_b32_dpp v134, v178 row_ror:1 row_mask:0xf bank_mask:0xf
	v_mov_b32_dpp v135, v179 row_ror:1 row_mask:0xf bank_mask:0xf
	v_pk_fma_f32 v[142:143], v[66:67], v[156:157], v[132:133] op_sel_hi:[1,0,1]
	v_pk_fma_f32 v[186:187], v[68:69], v[156:157], v[130:131] op_sel_hi:[1,0,1]
	v_cndmask_b32_e64 v189, v135, v218, s[42:43]
	v_cndmask_b32_e64 v188, v134, v217, s[42:43]
	v_mov_b32_dpp v203, v176 row_ror:2 row_mask:0xf bank_mask:0xf
	v_mov_b32_dpp v210, v177 row_ror:2 row_mask:0xf bank_mask:0xf
	s_waitcnt lgkmcnt(0)
	v_pk_fma_f32 v[136:137], v[190:191], v[126:127], v[82:83]
	v_mov_b32_dpp v201, v176 row_ror:1 row_mask:0xf bank_mask:0xf
	v_mov_b32_dpp v202, v177 row_ror:1 row_mask:0xf bank_mask:0xf
	v_pk_fma_f32 v[136:137], v[188:189], v[86:87], v[136:137]
	v_cndmask_b32_e32 v155, v216, v210, vcc
	v_cndmask_b32_e32 v154, v215, v203, vcc
	v_cndmask_b32_e64 v141, v202, v214, s[42:43]
	v_cndmask_b32_e64 v140, v201, v209, s[42:43]
	v_pk_fma_f32 v[134:135], v[154:155], v[124:125], v[80:81]
	v_pk_fma_f32 v[132:133], v[178:179], v[122:123], v[136:137]
	v_pk_fma_f32 v[134:135], v[140:141], v[84:85], v[134:135]
	v_pk_mul_f32 v[136:137], v[132:133], s[20:21] op_sel_hi:[1,0]
	v_pk_fma_f32 v[130:131], v[176:177], v[120:121], v[134:135]
	v_exp_f32_e32 v136, v136
	v_pk_mul_f32 v[134:135], v[130:131], s[20:21] op_sel_hi:[1,0]
	v_exp_f32_e32 v137, v137
	v_exp_f32_e32 v134, v134
	v_exp_f32_e32 v135, v135
	v_pk_mul_f32 v[132:133], v[142:143], v[132:133]
	v_pk_add_f32 v[136:137], v[136:137], 1.0 op_sel_hi:[1,0]
	v_pk_mul_f32 v[130:131], v[184:185], v[130:131]
	v_pk_add_f32 v[134:135], v[134:135], 1.0 op_sel_hi:[1,0]
	v_rcp_f32_e32 v136, v136
	v_rcp_f32_e32 v137, v137
	v_rcp_f32_e32 v134, v134
	v_rcp_f32_e32 v135, v135
	v_pk_mul_f32 v[142:143], v[132:133], v[136:137]
	v_pk_mul_f32 v[152:153], v[130:131], v[134:135]
	ds_read_b128 v[72:75], v147 offset:1536
	ds_read_b128 v[76:79], v147 offset:512
	v_mov_b32_dpp v199, v164 row_ror:2 row_mask:0xf bank_mask:0xf
	v_mov_b32_dpp v200, v165 row_ror:2 row_mask:0xf bank_mask:0xf
	v_mov_b32_dpp v197, v164 row_ror:1 row_mask:0xf bank_mask:0xf
	v_mov_b32_dpp v198, v165 row_ror:1 row_mask:0xf bank_mask:0xf
	v_cndmask_b32_e32 v177, v208, v200, vcc
	v_cndmask_b32_e32 v176, v207, v199, vcc
	v_mov_b32_dpp v194, v163 row_ror:1 row_mask:0xf bank_mask:0xf
	v_mov_b32_dpp v195, v162 row_ror:2 row_mask:0xf bank_mask:0xf
	v_mov_b32_dpp v196, v163 row_ror:2 row_mask:0xf bank_mask:0xf
	v_cndmask_b32_e64 v155, v198, v206, s[42:43]
	v_cndmask_b32_e64 v154, v197, v205, s[42:43]
	s_waitcnt lgkmcnt(0)
	v_pk_fma_f32 v[136:137], v[176:177], v[114:115], v[74:75]
	v_mov_b32_dpp v129, v162 row_ror:1 row_mask:0xf bank_mask:0xf
	v_pk_fma_f32 v[136:137], v[154:155], v[78:79], v[136:137]
	v_cndmask_b32_e64 v141, v194, v146, s[42:43]
	v_cndmask_b32_e32 v147, v204, v196, vcc
	v_cndmask_b32_e32 v146, v145, v195, vcc
	v_cndmask_b32_e64 v140, v129, v144, s[42:43]
	v_pk_fma_f32 v[134:135], v[146:147], v[112:113], v[72:73]
	v_pk_fma_f32 v[132:133], v[164:165], v[118:119], v[136:137]
	v_pk_fma_f32 v[134:135], v[140:141], v[76:77], v[134:135]
	v_pk_mul_f32 v[136:137], v[132:133], s[20:21] op_sel_hi:[1,0]
	v_pk_fma_f32 v[130:131], v[162:163], v[116:117], v[134:135]
	v_exp_f32_e32 v136, v136
	v_pk_mul_f32 v[134:135], v[130:131], s[20:21] op_sel_hi:[1,0]
	v_exp_f32_e32 v137, v137
	v_exp_f32_e32 v134, v134
	v_exp_f32_e32 v135, v135
	s_xor_b64 s[8:9], s[48:49], -1
	v_pk_add_f32 v[136:137], v[136:137], 1.0 op_sel_hi:[1,0]
	v_cndmask_b32_e64 v128, 0, 1, s[8:9]
	v_pk_add_f32 v[134:135], v[134:135], 1.0 op_sel_hi:[1,0]
	v_rcp_f32_e32 v136, v136
	v_rcp_f32_e32 v137, v137
	v_rcp_f32_e32 v134, v134
	v_rcp_f32_e32 v135, v135
	s_and_b64 s[8:9], s[48:49], exec
	s_cselect_b32 s5, 2, 0
	v_or_b32_e32 v128, s5, v128
	v_pk_mul_f32 v[132:133], v[180:181], v[132:133]
	v_pk_mul_f32 v[130:131], v[186:187], v[130:131]
	v_add_u32_e32 v129, s4, v173
	v_lshlrev_b32_e32 v128, 10, v128
	v_pk_mul_f32 v[132:133], v[132:133], v[136:137]
	v_pk_mul_f32 v[130:131], v[130:131], v[134:135]
	v_mad_i64_i32 v[134:135], s[8:9], v129, s19, v[148:149]
	v_add_u32_e32 v128, 0, v128
	v_cvt_pk_bf16_f32 v130, v130, v131
	v_cvt_pk_bf16_f32 v131, v132, v133
	v_cvt_pk_bf16_f32 v132, v152, v153
	v_cvt_pk_bf16_f32 v133, v142, v143
	v_lshl_add_u64 v[134:135], v[134:135], 0, v[150:151]
	v_lshl_add_u32 v128, v171, 2, v128
	global_store_dwordx4 v[134:135], v[130:133], off
	v_add_u32_e32 v136, 0x20000, v128
	v_add_u32_e32 v214, 0x80, v160
	ds_read_b128 v[128:131], v136
	ds_read_b128 v[140:143], v136 offset:16
	ds_read_b128 v[132:135], v136 offset:512
	ds_read_b128 v[144:147], v136 offset:528
	v_mov_b32_e32 v215, v167
	v_lshl_add_u32 v136, v214, 3, s67
	ds_read_b64 v[136:137], v136
	s_waitcnt lgkmcnt(0)
	v_pk_mul_f32 v[156:157], v[136:137], s[96:97] op_sel_hi:[1,0]
	v_cndmask_b32_e64 v142, v142, v146, s[44:45]
	v_fma_f32 v136, -v156, v156, v157
	v_max_f32_e32 v136, 0, v136
	v_add_f32_e32 v136, 0x3727c5ac, v136
	v_rsq_f32_e32 v158, v136
	v_cndmask_b32_e64 v143, v143, v147, s[44:45]
	v_cndmask_b32_e64 v140, v140, v144, s[44:45]
	v_mul_f32_e64 v180, v158, -v156
	s_waitcnt lgkmcnt(0)
	v_pk_fma_f32 v[136:137], v[222:223], v[180:181], v[226:227] op_sel_hi:[1,0,1]
	v_cndmask_b32_e64 v141, v141, v145, s[44:45]
	v_pk_fma_f32 v[152:153], v[60:61], v[158:159], v[136:137] op_sel_hi:[1,0,1]
	v_pk_fma_f32 v[136:137], v[224:225], v[180:181], v[228:229] op_sel_hi:[1,0,1]
	v_pk_fma_f32 v[154:155], v[232:233], v[180:181], v[236:237] op_sel_hi:[1,0,1]
	v_pk_fma_f32 v[156:157], v[62:63], v[158:159], v[136:137] op_sel_hi:[1,0,1]
	v_pk_fma_f32 v[136:137], v[230:231], v[180:181], v[234:235] op_sel_hi:[1,0,1]
	v_pk_fma_f32 v[206:207], v[58:59], v[158:159], v[154:155] op_sel_hi:[1,0,1]
	v_pk_fma_f32 v[190:191], v[56:57], v[158:159], v[136:137] op_sel_hi:[1,0,1]
	s_nop 0
	v_mov_b32_dpp v188, v206 row_ror:2 row_mask:0xf bank_mask:0xf
	v_mov_b32_dpp v189, v207 row_ror:2 row_mask:0xf bank_mask:0xf
	v_mov_b32_dpp v216, v206 row_ror:1 row_mask:0xf bank_mask:0xf
	s_waitcnt lgkmcnt(0)
	v_pk_fma_f32 v[138:139], v[240:241], v[180:181], v[246:247] op_sel_hi:[1,0,1]
	v_pk_fma_f32 v[136:137], v[238:239], v[180:181], v[244:245] op_sel_hi:[1,0,1]
	v_pk_fma_f32 v[154:155], v[30:31], v[158:159], v[138:139] op_sel_hi:[1,0,1]
	v_pk_fma_f32 v[138:139], v[88:89], v[180:181], v[92:93] op_sel_hi:[1,0,1]
	v_pk_fma_f32 v[208:209], v[24:25], v[158:159], v[138:139] op_sel_hi:[1,0,1]
	v_pk_fma_f32 v[138:139], v[90:91], v[180:181], v[94:95] op_sel_hi:[1,0,1]
	v_pk_fma_f32 v[210:211], v[26:27], v[158:159], v[138:139] op_sel_hi:[1,0,1]
	v_pk_fma_f32 v[158:159], v[28:29], v[158:159], v[136:137] op_sel_hi:[1,0,1]
	v_mov_b32_dpp v217, v207 row_ror:1 row_mask:0xf bank_mask:0xf
	v_cndmask_b32_e32 v143, v143, v189, vcc
	v_cndmask_b32_e32 v142, v142, v188, vcc
	v_mov_b32_dpp v185, v190 row_ror:2 row_mask:0xf bank_mask:0xf
	v_mov_b32_dpp v187, v191 row_ror:2 row_mask:0xf bank_mask:0xf
	v_cndmask_b32_e64 v213, v217, v147, s[42:43]
	v_cndmask_b32_e64 v212, v216, v146, s[42:43]
	s_waitcnt lgkmcnt(0)
	v_pk_fma_f32 v[142:143], v[142:143], v[126:127], v[82:83]
	v_mov_b32_dpp v184, v190 row_ror:1 row_mask:0xf bank_mask:0xf
	v_mov_b32_dpp v186, v191 row_ror:1 row_mask:0xf bank_mask:0xf
	v_pk_fma_f32 v[142:143], v[212:213], v[86:87], v[142:143]
	v_cndmask_b32_e32 v141, v141, v187, vcc
	v_cndmask_b32_e32 v140, v140, v185, vcc
	v_pk_fma_f32 v[142:143], v[206:207], v[122:123], v[142:143]
	v_cndmask_b32_e64 v165, v186, v145, s[42:43]
	v_cndmask_b32_e64 v164, v184, v144, s[42:43]
	v_pk_fma_f32 v[140:141], v[140:141], v[124:125], v[80:81]
	v_pk_mul_f32 v[146:147], v[142:143], s[20:21] op_sel_hi:[1,0]
	v_pk_fma_f32 v[140:141], v[164:165], v[84:85], v[140:141]
	v_exp_f32_e32 v146, v146
	v_pk_fma_f32 v[140:141], v[190:191], v[120:121], v[140:141]
	v_exp_f32_e32 v147, v147
	v_pk_mul_f32 v[144:145], v[140:141], s[20:21] op_sel_hi:[1,0]
	v_pk_mul_f32 v[142:143], v[210:211], v[142:143]
	v_exp_f32_e32 v144, v144
	v_exp_f32_e32 v145, v145
	v_pk_add_f32 v[146:147], v[146:147], 1.0 op_sel_hi:[1,0]
	v_pk_mul_f32 v[140:141], v[208:209], v[140:141]
	v_rcp_f32_e32 v146, v146
	v_pk_add_f32 v[144:145], v[144:145], 1.0 op_sel_hi:[1,0]
	v_rcp_f32_e32 v147, v147
	v_rcp_f32_e32 v144, v144
	v_rcp_f32_e32 v145, v145
	v_pk_mul_f32 v[162:163], v[142:143], v[146:147]
	v_pk_mul_f32 v[164:165], v[140:141], v[144:145]
	v_mov_b32_dpp v173, v152 row_ror:2 row_mask:0xf bank_mask:0xf
	v_mov_b32_dpp v177, v153 row_ror:2 row_mask:0xf bank_mask:0xf
	v_mov_b32_dpp v179, v156 row_ror:2 row_mask:0xf bank_mask:0xf
	v_mov_b32_dpp v180, v157 row_ror:2 row_mask:0xf bank_mask:0xf
	v_cndmask_b32_e64 v130, v130, v134, s[44:45]
	v_cndmask_b32_e64 v131, v131, v135, s[44:45]
	v_cndmask_b32_e64 v128, v128, v132, s[44:45]
	v_cndmask_b32_e64 v129, v129, v133, s[44:45]
	v_mov_b32_dpp v171, v152 row_ror:1 row_mask:0xf bank_mask:0xf
	v_mov_b32_dpp v176, v153 row_ror:1 row_mask:0xf bank_mask:0xf
	v_cndmask_b32_e32 v131, v131, v180, vcc
	v_cndmask_b32_e32 v130, v130, v179, vcc
	v_cndmask_b32_e32 v129, v129, v177, vcc
	v_cndmask_b32_e32 v128, v128, v173, vcc
	v_mov_b32_dpp v178, v156 row_ror:1 row_mask:0xf bank_mask:0xf
	v_mov_b32_dpp v181, v157 row_ror:1 row_mask:0xf bank_mask:0xf
	s_waitcnt lgkmcnt(0)
	v_pk_fma_f32 v[130:131], v[130:131], v[114:115], v[74:75]
	v_cndmask_b32_e64 v139, v176, v133, s[42:43]
	v_cndmask_b32_e64 v138, v171, v132, s[42:43]
	v_pk_fma_f32 v[128:129], v[128:129], v[112:113], v[72:73]
	v_cndmask_b32_e64 v191, v181, v135, s[42:43]
	v_cndmask_b32_e64 v190, v178, v134, s[42:43]
	v_pk_fma_f32 v[128:129], v[138:139], v[76:77], v[128:129]
	v_pk_fma_f32 v[130:131], v[190:191], v[78:79], v[130:131]
	v_pk_fma_f32 v[128:129], v[152:153], v[116:117], v[128:129]
	v_pk_fma_f32 v[130:131], v[156:157], v[118:119], v[130:131]
	v_pk_mul_f32 v[132:133], v[128:129], s[20:21] op_sel_hi:[1,0]
	v_pk_mul_f32 v[134:135], v[130:131], s[20:21] op_sel_hi:[1,0]
	v_exp_f32_e32 v132, v132
	v_exp_f32_e32 v133, v133
	v_exp_f32_e32 v134, v134
	v_exp_f32_e32 v135, v135
	v_pk_mul_f32 v[128:129], v[158:159], v[128:129]
	v_pk_add_f32 v[132:133], v[132:133], 1.0 op_sel_hi:[1,0]
	v_pk_mul_f32 v[130:131], v[154:155], v[130:131]
	v_pk_add_f32 v[134:135], v[134:135], 1.0 op_sel_hi:[1,0]
	v_rcp_f32_e32 v132, v132
	v_rcp_f32_e32 v133, v133
	v_rcp_f32_e32 v134, v134
	v_rcp_f32_e32 v135, v135
	v_add_u32_e32 v208, 0x90, v160
	v_pk_mul_f32 v[128:129], v[128:129], v[132:133]
	v_add_u32_e32 v132, s4, v214
	v_pk_mul_f32 v[130:131], v[130:131], v[134:135]
	v_mad_i64_i32 v[132:133], s[8:9], v132, s19, v[148:149]
	v_cvt_pk_bf16_f32 v128, v128, v129
	v_cvt_pk_bf16_f32 v129, v130, v131
	v_cvt_pk_bf16_f32 v130, v164, v165
	v_cvt_pk_bf16_f32 v131, v162, v163
	v_lshl_add_u64 v[132:133], v[132:133], 0, v[150:151]
	global_store_dwordx4 v[132:133], v[128:131], off nt
	v_mov_b32_e32 v209, v167
	s_nop 0
	v_lshl_add_u32 v128, v208, 3, s67
	ds_read_b64 v[128:129], v128
	s_waitcnt lgkmcnt(0)
	v_pk_mul_f32 v[136:137], v[128:129], s[96:97] op_sel_hi:[1,0]
	v_fma_f32 v128, -v136, v136, v137
	v_max_f32_e32 v128, 0, v128
	v_add_f32_e32 v128, 0x3727c5ac, v128
	v_rsq_f32_e32 v156, v128
	s_nop 0
	v_mul_f32_e64 v146, v156, -v136
	s_waitcnt lgkmcnt(0)
	v_pk_fma_f32 v[128:129], v[222:223], v[146:147], v[226:227] op_sel_hi:[1,0,1]
	v_mov_b32_e32 v218, v161
	v_pk_fma_f32 v[132:133], v[52:53], v[156:157], v[128:129] op_sel_hi:[1,0,1]
	v_pk_fma_f32 v[128:129], v[224:225], v[146:147], v[228:229] op_sel_hi:[1,0,1]
	v_pk_fma_f32 v[134:135], v[232:233], v[146:147], v[236:237] op_sel_hi:[1,0,1]
	v_pk_fma_f32 v[136:137], v[54:55], v[156:157], v[128:129] op_sel_hi:[1,0,1]
	v_pk_fma_f32 v[128:129], v[230:231], v[146:147], v[234:235] op_sel_hi:[1,0,1]
	v_pk_fma_f32 v[200:201], v[50:51], v[156:157], v[134:135] op_sel_hi:[1,0,1]
	v_pk_fma_f32 v[190:191], v[48:49], v[156:157], v[128:129] op_sel_hi:[1,0,1]
	s_nop 0
	v_mov_b32_dpp v214, v200 row_ror:2 row_mask:0xf bank_mask:0xf
	v_mov_b32_dpp v215, v201 row_ror:2 row_mask:0xf bank_mask:0xf
	v_mov_b32_dpp v210, v191 row_ror:1 row_mask:0xf bank_mask:0xf
	s_waitcnt lgkmcnt(0)
	v_pk_fma_f32 v[130:131], v[240:241], v[146:147], v[246:247] op_sel_hi:[1,0,1]
	v_pk_fma_f32 v[128:129], v[238:239], v[146:147], v[244:245] op_sel_hi:[1,0,1]
	v_pk_fma_f32 v[134:135], v[22:23], v[156:157], v[130:131] op_sel_hi:[1,0,1]
	v_pk_fma_f32 v[130:131], v[88:89], v[146:147], v[92:93] op_sel_hi:[1,0,1]
	v_pk_fma_f32 v[138:139], v[20:21], v[156:157], v[128:129] op_sel_hi:[1,0,1]
	v_pk_fma_f32 v[202:203], v[16:17], v[156:157], v[130:131] op_sel_hi:[1,0,1]
	v_pk_fma_f32 v[130:131], v[90:91], v[146:147], v[94:95] op_sel_hi:[1,0,1]
	v_pk_fma_f32 v[204:205], v[18:19], v[156:157], v[130:131] op_sel_hi:[1,0,1]
	v_mov_b32_dpp v195, v190 row_ror:2 row_mask:0xf bank_mask:0xf
	v_mov_b32_dpp v211, v191 row_ror:2 row_mask:0xf bank_mask:0xf
	v_cndmask_b32_e32 v189, v189, v215, vcc
	v_cndmask_b32_e32 v188, v188, v214, vcc
	v_mov_b32_dpp v194, v190 row_ror:1 row_mask:0xf bank_mask:0xf
	v_mov_b32_dpp v212, v200 row_ror:1 row_mask:0xf bank_mask:0xf
	v_mov_b32_dpp v213, v201 row_ror:1 row_mask:0xf bank_mask:0xf
	s_waitcnt lgkmcnt(0)
	v_pk_fma_f32 v[158:159], v[188:189], v[126:127], v[82:83]
	v_cndmask_b32_e64 v165, v210, v186, s[42:43]
	v_cndmask_b32_e32 v187, v187, v211, vcc
	v_cndmask_b32_e32 v186, v185, v195, vcc
	v_cndmask_b32_e64 v207, v213, v217, s[42:43]
	v_cndmask_b32_e64 v206, v212, v216, s[42:43]
	v_cndmask_b32_e64 v164, v194, v184, s[42:43]
	v_pk_fma_f32 v[156:157], v[186:187], v[124:125], v[80:81]
	v_pk_fma_f32 v[158:159], v[206:207], v[86:87], v[158:159]
	v_pk_fma_f32 v[156:157], v[164:165], v[84:85], v[156:157]
	v_pk_fma_f32 v[142:143], v[200:201], v[122:123], v[158:159]
	v_pk_fma_f32 v[156:157], v[190:191], v[120:121], v[156:157]
	v_pk_mul_f32 v[158:159], v[142:143], s[20:21] op_sel_hi:[1,0]
	v_pk_mul_f32 v[140:141], v[156:157], s[20:21] op_sel_hi:[1,0]
	v_exp_f32_e32 v158, v158
	v_exp_f32_e32 v159, v159
	v_exp_f32_e32 v140, v140
	v_exp_f32_e32 v141, v141
	v_pk_add_f32 v[158:159], v[158:159], 1.0 op_sel_hi:[1,0]
	v_pk_add_f32 v[140:141], v[140:141], 1.0 op_sel_hi:[1,0]
	v_rcp_f32_e32 v158, v158
	v_rcp_f32_e32 v159, v159
	v_rcp_f32_e32 v162, v140
	v_rcp_f32_e32 v163, v141
	v_pk_mul_f32 v[140:141], v[204:205], v[142:143]
	v_pk_mul_f32 v[142:143], v[202:203], v[156:157]
	v_pk_mul_f32 v[140:141], v[140:141], v[158:159]
	v_pk_mul_f32 v[142:143], v[142:143], v[162:163]
	v_mov_b32_dpp v155, v137 row_ror:1 row_mask:0xf bank_mask:0xf
	v_mov_b32_dpp v153, v136 row_ror:2 row_mask:0xf bank_mask:0xf
	v_mov_b32_dpp v154, v137 row_ror:2 row_mask:0xf bank_mask:0xf
	v_mov_b32_dpp v152, v136 row_ror:1 row_mask:0xf bank_mask:0xf
	v_cndmask_b32_e64 v189, v155, v181, s[42:43]
	v_cndmask_b32_e32 v181, v180, v154, vcc
	v_cndmask_b32_e32 v180, v179, v153, vcc
	v_mov_b32_dpp v145, v132 row_ror:2 row_mask:0xf bank_mask:0xf
	v_mov_b32_dpp v147, v133 row_ror:2 row_mask:0xf bank_mask:0xf
	v_cndmask_b32_e64 v188, v152, v178, s[42:43]
	s_waitcnt lgkmcnt(0)
	v_pk_fma_f32 v[130:131], v[180:181], v[114:115], v[74:75]
	v_mov_b32_dpp v144, v132 row_ror:1 row_mask:0xf bank_mask:0xf
	v_mov_b32_dpp v146, v133 row_ror:1 row_mask:0xf bank_mask:0xf
	v_pk_fma_f32 v[130:131], v[188:189], v[78:79], v[130:131]
	v_cndmask_b32_e32 v165, v177, v147, vcc
	v_cndmask_b32_e32 v164, v173, v145, vcc
	v_pk_fma_f32 v[130:131], v[136:137], v[118:119], v[130:131]
	v_cndmask_b32_e64 v159, v146, v176, s[42:43]
	v_cndmask_b32_e64 v158, v144, v171, s[42:43]
	v_pk_fma_f32 v[128:129], v[164:165], v[112:113], v[72:73]
	v_pk_mul_f32 v[136:137], v[130:131], s[20:21] op_sel_hi:[1,0]
	v_pk_fma_f32 v[128:129], v[158:159], v[76:77], v[128:129]
	v_exp_f32_e32 v136, v136
	v_pk_fma_f32 v[128:129], v[132:133], v[116:117], v[128:129]
	v_exp_f32_e32 v137, v137
	v_pk_mul_f32 v[132:133], v[128:129], s[20:21] op_sel_hi:[1,0]
	v_pk_mul_f32 v[128:129], v[138:139], v[128:129]
	v_exp_f32_e32 v132, v132
	v_exp_f32_e32 v133, v133
	v_pk_add_f32 v[136:137], v[136:137], 1.0 op_sel_hi:[1,0]
	v_pk_mul_f32 v[130:131], v[134:135], v[130:131]
	v_rcp_f32_e32 v136, v136
	v_pk_add_f32 v[132:133], v[132:133], 1.0 op_sel_hi:[1,0]
	v_rcp_f32_e32 v137, v137
	v_rcp_f32_e32 v132, v132
	v_rcp_f32_e32 v133, v133
	v_add_u32_e32 v179, 0xa0, v160
	v_pk_mul_f32 v[130:131], v[130:131], v[136:137]
	v_mov_b32_e32 v216, v167
	v_pk_mul_f32 v[128:129], v[128:129], v[132:133]
	v_add_u32_e32 v132, s4, v208
	v_mad_i64_i32 v[132:133], s[8:9], v132, s19, v[148:149]
	v_cvt_pk_bf16_f32 v128, v128, v129
	v_cvt_pk_bf16_f32 v129, v130, v131
	v_cvt_pk_bf16_f32 v130, v142, v143
	v_cvt_pk_bf16_f32 v131, v140, v141
	v_lshl_add_u64 v[132:133], v[132:133], 0, v[150:151]
	global_store_dwordx4 v[132:133], v[128:131], off nt
	s_nop 1
	v_lshl_add_u32 v128, v179, 3, s67
	ds_read_b64 v[128:129], v128
	s_and_b64 s[24:25], s[86:87], s[48:49]
	s_waitcnt lgkmcnt(0)
	v_pk_mul_f32 v[136:137], v[128:129], s[96:97] op_sel_hi:[1,0]
	s_nop 0
	v_fma_f32 v128, -v136, v136, v137
	v_max_f32_e32 v128, 0, v128
	v_add_f32_e32 v128, 0x3727c5ac, v128
	v_rsq_f32_e32 v142, v128
	s_nop 0
	v_mul_f32_e64 v176, v142, -v136
	s_waitcnt lgkmcnt(0)
	v_pk_fma_f32 v[128:129], v[222:223], v[176:177], v[226:227] op_sel_hi:[1,0,1]
	s_nop 0
	v_pk_fma_f32 v[132:133], v[44:45], v[142:143], v[128:129] op_sel_hi:[1,0,1]
	v_pk_fma_f32 v[128:129], v[224:225], v[176:177], v[228:229] op_sel_hi:[1,0,1]
	v_pk_fma_f32 v[134:135], v[232:233], v[176:177], v[236:237] op_sel_hi:[1,0,1]
	v_pk_fma_f32 v[136:137], v[46:47], v[142:143], v[128:129] op_sel_hi:[1,0,1]
	v_pk_fma_f32 v[128:129], v[230:231], v[176:177], v[234:235] op_sel_hi:[1,0,1]
	v_pk_fma_f32 v[188:189], v[42:43], v[142:143], v[134:135] op_sel_hi:[1,0,1]
	v_pk_fma_f32 v[180:181], v[40:41], v[142:143], v[128:129] op_sel_hi:[1,0,1]
	v_mov_b32_dpp v218, v133 row_ror:1 row_mask:0xf bank_mask:0xf
	v_mov_b32_dpp v219, v133 row_ror:2 row_mask:0xf bank_mask:0xf
	v_mov_b32_dpp v173, v136 row_ror:2 row_mask:0xf bank_mask:0xf
	s_waitcnt lgkmcnt(0)
	v_pk_fma_f32 v[130:131], v[240:241], v[176:177], v[246:247] op_sel_hi:[1,0,1]
	v_pk_fma_f32 v[128:129], v[238:239], v[176:177], v[244:245] op_sel_hi:[1,0,1]
	v_pk_fma_f32 v[134:135], v[14:15], v[142:143], v[130:131] op_sel_hi:[1,0,1]
	v_pk_fma_f32 v[130:131], v[88:89], v[176:177], v[92:93] op_sel_hi:[1,0,1]
	v_pk_fma_f32 v[190:191], v[8:9], v[142:143], v[130:131] op_sel_hi:[1,0,1]
	v_pk_fma_f32 v[130:131], v[90:91], v[176:177], v[94:95] op_sel_hi:[1,0,1]
	v_pk_fma_f32 v[204:205], v[10:11], v[142:143], v[130:131] op_sel_hi:[1,0,1]
	v_pk_fma_f32 v[138:139], v[12:13], v[142:143], v[128:129] op_sel_hi:[1,0,1]
	v_mov_b32_dpp v156, v188 row_ror:2 row_mask:0xf bank_mask:0xf
	v_mov_b32_dpp v157, v189 row_ror:2 row_mask:0xf bank_mask:0xf
	v_mov_b32_dpp v158, v188 row_ror:1 row_mask:0xf bank_mask:0xf
	v_mov_b32_dpp v159, v189 row_ror:1 row_mask:0xf bank_mask:0xf
	v_cndmask_b32_e32 v209, v215, v157, vcc
	v_cndmask_b32_e32 v208, v214, v156, vcc
	v_mov_b32_dpp v163, v180 row_ror:2 row_mask:0xf bank_mask:0xf
	v_mov_b32_dpp v164, v181 row_ror:2 row_mask:0xf bank_mask:0xf
	v_cndmask_b32_e64 v207, v159, v213, s[42:43]
	v_cndmask_b32_e64 v206, v158, v212, s[42:43]
	s_waitcnt lgkmcnt(0)
	v_pk_fma_f32 v[186:187], v[208:209], v[126:127], v[82:83]
	v_mov_b32_dpp v162, v180 row_ror:1 row_mask:0xf bank_mask:0xf
	v_mov_b32_dpp v165, v181 row_ror:1 row_mask:0xf bank_mask:0xf
	v_pk_fma_f32 v[186:187], v[206:207], v[86:87], v[186:187]
	v_cndmask_b32_e32 v199, v211, v164, vcc
	v_cndmask_b32_e32 v198, v195, v163, vcc
	v_pk_fma_f32 v[142:143], v[188:189], v[122:123], v[186:187]
	v_cndmask_b32_e64 v189, v165, v210, s[42:43]
	v_cndmask_b32_e64 v188, v162, v194, s[42:43]
	v_pk_fma_f32 v[184:185], v[198:199], v[124:125], v[80:81]
	v_pk_mul_f32 v[186:187], v[142:143], s[20:21] op_sel_hi:[1,0]
	v_pk_fma_f32 v[184:185], v[188:189], v[84:85], v[184:185]
	v_exp_f32_e32 v186, v186
	v_pk_fma_f32 v[180:181], v[180:181], v[120:121], v[184:185]
	v_exp_f32_e32 v187, v187
	v_pk_mul_f32 v[140:141], v[180:181], s[20:21] op_sel_hi:[1,0]
	v_exp_f32_e32 v140, v140
	v_exp_f32_e32 v141, v141
	v_pk_add_f32 v[184:185], v[186:187], 1.0 op_sel_hi:[1,0]
	v_rcp_f32_e32 v184, v184
	v_pk_add_f32 v[140:141], v[140:141], 1.0 op_sel_hi:[1,0]
	v_rcp_f32_e32 v185, v185
	v_rcp_f32_e32 v186, v140
	v_rcp_f32_e32 v187, v141
	v_pk_mul_f32 v[140:141], v[204:205], v[142:143]
	v_pk_mul_f32 v[142:143], v[190:191], v[180:181]
	v_pk_mul_f32 v[140:141], v[140:141], v[184:185]
	v_pk_mul_f32 v[142:143], v[142:143], v[186:187]
	v_mov_b32_dpp v177, v132 row_ror:2 row_mask:0xf bank_mask:0xf
	v_mov_b32_dpp v176, v137 row_ror:1 row_mask:0xf bank_mask:0xf
	v_mov_b32_dpp v178, v137 row_ror:2 row_mask:0xf bank_mask:0xf
	v_mov_b32_dpp v217, v132 row_ror:1 row_mask:0xf bank_mask:0xf
	v_mov_b32_dpp v171, v136 row_ror:1 row_mask:0xf bank_mask:0xf
	v_cndmask_b32_e64 v181, v176, v155, s[42:43]
	v_cndmask_b32_e32 v155, v154, v178, vcc
	v_cndmask_b32_e32 v154, v153, v173, vcc
	v_cndmask_b32_e64 v153, v218, v146, s[42:43]
	v_cndmask_b32_e32 v147, v147, v219, vcc
	v_cndmask_b32_e32 v146, v145, v177, vcc
	v_cndmask_b32_e64 v180, v171, v152, s[42:43]
	v_cndmask_b32_e64 v152, v217, v144, s[42:43]
	s_waitcnt lgkmcnt(0)
	v_pk_fma_f32 v[128:129], v[146:147], v[112:113], v[72:73]
	v_pk_fma_f32 v[130:131], v[154:155], v[114:115], v[74:75]
	v_pk_fma_f32 v[128:129], v[152:153], v[76:77], v[128:129]
	v_pk_fma_f32 v[130:131], v[180:181], v[78:79], v[130:131]
	v_pk_fma_f32 v[128:129], v[132:133], v[116:117], v[128:129]
	v_pk_fma_f32 v[130:131], v[136:137], v[118:119], v[130:131]
	v_pk_mul_f32 v[132:133], v[128:129], s[20:21] op_sel_hi:[1,0]
	v_pk_mul_f32 v[136:137], v[130:131], s[20:21] op_sel_hi:[1,0]
	v_exp_f32_e32 v132, v132
	v_exp_f32_e32 v133, v133
	v_exp_f32_e32 v136, v136
	v_exp_f32_e32 v137, v137
	v_pk_mul_f32 v[128:129], v[138:139], v[128:129]
	v_pk_add_f32 v[132:133], v[132:133], 1.0 op_sel_hi:[1,0]
	v_pk_mul_f32 v[130:131], v[134:135], v[130:131]
	v_pk_add_f32 v[136:137], v[136:137], 1.0 op_sel_hi:[1,0]
	v_rcp_f32_e32 v132, v132
	v_rcp_f32_e32 v133, v133
	v_rcp_f32_e32 v136, v136
	v_rcp_f32_e32 v137, v137
	v_add_u32_e32 v200, 0xb0, v160
	v_pk_mul_f32 v[128:129], v[128:129], v[132:133]
	v_add_u32_e32 v132, s4, v179
	v_pk_mul_f32 v[130:131], v[130:131], v[136:137]
	v_mad_i64_i32 v[132:133], s[8:9], v132, s19, v[148:149]
	v_cvt_pk_bf16_f32 v128, v128, v129
	v_cvt_pk_bf16_f32 v129, v130, v131
	v_cvt_pk_bf16_f32 v130, v142, v143
	v_cvt_pk_bf16_f32 v131, v140, v141
	v_lshl_add_u64 v[132:133], v[132:133], 0, v[150:151]
	global_store_dwordx4 v[132:133], v[128:131], off nt
	v_mov_b32_e32 v201, v167
	s_nop 0
	v_lshl_add_u32 v128, v200, 3, s67
	ds_read_b64 v[128:129], v128
	s_waitcnt lgkmcnt(0)
	v_pk_mul_f32 v[144:145], v[128:129], s[96:97] op_sel_hi:[1,0]
	v_fma_f32 v128, -v144, v144, v145
	v_max_f32_e32 v128, 0, v128
	v_add_f32_e32 v128, 0x3727c5ac, v128
	v_rsq_f32_e32 v160, v128
	s_nop 0
	v_mul_f32_e64 v180, v160, -v144
	s_waitcnt lgkmcnt(0)
	v_pk_fma_f32 v[128:129], v[222:223], v[180:181], v[226:227] op_sel_hi:[1,0,1]
	v_pk_fma_f32 v[130:131], v[224:225], v[180:181], v[228:229] op_sel_hi:[1,0,1]
	v_pk_fma_f32 v[132:133], v[230:231], v[180:181], v[234:235] op_sel_hi:[1,0,1]
	v_pk_fma_f32 v[134:135], v[232:233], v[180:181], v[236:237] op_sel_hi:[1,0,1]
	v_pk_fma_f32 v[128:129], v[36:37], v[160:161], v[128:129] op_sel_hi:[1,0,1]
	v_pk_fma_f32 v[130:131], v[38:39], v[160:161], v[130:131] op_sel_hi:[1,0,1]
	s_waitcnt lgkmcnt(0)
	v_pk_fma_f32 v[152:153], v[238:239], v[180:181], v[244:245] op_sel_hi:[1,0,1]
	v_pk_fma_f32 v[144:145], v[240:241], v[180:181], v[246:247] op_sel_hi:[1,0,1]
	v_pk_fma_f32 v[136:137], v[88:89], v[180:181], v[92:93] op_sel_hi:[1,0,1]
	v_pk_fma_f32 v[188:189], v[6:7], v[160:161], v[144:145] op_sel_hi:[1,0,1]
	v_pk_fma_f32 v[144:145], v[0:1], v[160:161], v[136:137] op_sel_hi:[1,0,1]
	v_pk_fma_f32 v[136:137], v[90:91], v[180:181], v[94:95] op_sel_hi:[1,0,1]
	v_pk_fma_f32 v[180:181], v[4:5], v[160:161], v[152:153] op_sel_hi:[1,0,1]
	v_pk_fma_f32 v[146:147], v[2:3], v[160:161], v[136:137] op_sel_hi:[1,0,1]
	v_mov_b32_dpp v136, v128 row_ror:1 row_mask:0xf bank_mask:0xf
	v_mov_b32_dpp v137, v129 row_ror:1 row_mask:0xf bank_mask:0xf
	v_cndmask_b32_e64 v191, v137, v218, s[42:43]
	v_cndmask_b32_e64 v190, v136, v217, s[42:43]
	v_mov_b32_dpp v179, v128 row_ror:2 row_mask:0xf bank_mask:0xf
	v_mov_b32_dpp v198, v129 row_ror:2 row_mask:0xf bank_mask:0xf
	v_mov_b32_dpp v204, v130 row_ror:2 row_mask:0xf bank_mask:0xf
	v_mov_b32_dpp v205, v131 row_ror:2 row_mask:0xf bank_mask:0xf
	v_cndmask_b32_e32 v199, v219, v198, vcc
	v_cndmask_b32_e32 v198, v177, v179, vcc
	v_mov_b32_dpp v202, v130 row_ror:1 row_mask:0xf bank_mask:0xf
	v_mov_b32_dpp v203, v131 row_ror:1 row_mask:0xf bank_mask:0xf
	s_waitcnt lgkmcnt(0)
	v_pk_fma_f32 v[152:153], v[198:199], v[112:113], v[72:73]
	v_cndmask_b32_e32 v179, v178, v205, vcc
	v_cndmask_b32_e32 v178, v173, v204, vcc
	v_pk_fma_f32 v[152:153], v[190:191], v[76:77], v[152:153]
	v_cndmask_b32_e64 v177, v203, v176, s[42:43]
	v_cndmask_b32_e64 v176, v202, v171, s[42:43]
	v_pk_fma_f32 v[154:155], v[178:179], v[114:115], v[74:75]
	v_pk_fma_f32 v[140:141], v[128:129], v[116:117], v[152:153]
	v_pk_fma_f32 v[154:155], v[176:177], v[78:79], v[154:155]
	v_pk_mul_f32 v[152:153], v[140:141], s[20:21] op_sel_hi:[1,0]
	v_pk_fma_f32 v[142:143], v[130:131], v[118:119], v[154:155]
	v_exp_f32_e32 v152, v152
	v_exp_f32_e32 v153, v153
	v_pk_mul_f32 v[154:155], v[142:143], s[20:21] op_sel_hi:[1,0]
	v_pk_mul_f32 v[140:141], v[180:181], v[140:141]
	v_exp_f32_e32 v154, v154
	v_exp_f32_e32 v155, v155
	v_pk_add_f32 v[152:153], v[152:153], 1.0 op_sel_hi:[1,0]
	v_pk_fma_f32 v[132:133], v[32:33], v[160:161], v[132:133] op_sel_hi:[1,0,1]
	v_rcp_f32_e32 v152, v152
	v_rcp_f32_e32 v153, v153
	v_pk_add_f32 v[154:155], v[154:155], 1.0 op_sel_hi:[1,0]
	v_rcp_f32_e32 v154, v154
	v_rcp_f32_e32 v155, v155
	v_pk_mul_f32 v[152:153], v[140:141], v[152:153]
	v_pk_mul_f32 v[140:141], v[188:189], v[142:143]
	v_pk_mul_f32 v[154:155], v[140:141], v[154:155]
	v_mov_b32_dpp v207, v133 row_ror:1 row_mask:0xf bank_mask:0xf
	v_mov_b32_dpp v208, v132 row_ror:2 row_mask:0xf bank_mask:0xf
	v_mov_b32_dpp v209, v133 row_ror:2 row_mask:0xf bank_mask:0xf
	v_pk_fma_f32 v[134:135], v[34:35], v[160:161], v[134:135] op_sel_hi:[1,0,1]
	v_mov_b32_dpp v206, v132 row_ror:1 row_mask:0xf bank_mask:0xf
	v_cndmask_b32_e64 v181, v207, v165, s[42:43]
	v_cndmask_b32_e32 v165, v164, v209, vcc
	v_cndmask_b32_e32 v164, v163, v208, vcc
	v_mov_b32_dpp v212, v134 row_ror:2 row_mask:0xf bank_mask:0xf
	v_mov_b32_dpp v213, v135 row_ror:2 row_mask:0xf bank_mask:0xf
	v_cndmask_b32_e64 v180, v206, v162, s[42:43]
	s_waitcnt lgkmcnt(0)
	v_pk_fma_f32 v[136:137], v[164:165], v[124:125], v[80:81]
	v_mov_b32_dpp v210, v134 row_ror:1 row_mask:0xf bank_mask:0xf
	v_mov_b32_dpp v211, v135 row_ror:1 row_mask:0xf bank_mask:0xf
	v_pk_fma_f32 v[136:137], v[180:181], v[84:85], v[136:137]
	v_cndmask_b32_e32 v157, v157, v213, vcc
	v_cndmask_b32_e32 v156, v156, v212, vcc
	v_pk_fma_f32 v[136:137], v[132:133], v[120:121], v[136:137]
	v_cndmask_b32_e64 v159, v211, v159, s[42:43]
	v_cndmask_b32_e64 v158, v210, v158, s[42:43]
	v_pk_fma_f32 v[138:139], v[156:157], v[126:127], v[82:83]
	v_pk_mul_f32 v[140:141], v[136:137], s[20:21] op_sel_hi:[1,0]
	v_pk_fma_f32 v[138:139], v[158:159], v[86:87], v[138:139]
	v_exp_f32_e32 v140, v140
	v_exp_f32_e32 v141, v141
	v_pk_fma_f32 v[138:139], v[134:135], v[122:123], v[138:139]
	v_pk_mul_f32 v[136:137], v[144:145], v[136:137]
	v_pk_mul_f32 v[142:143], v[138:139], s[20:21] op_sel_hi:[1,0]
	v_pk_add_f32 v[140:141], v[140:141], 1.0 op_sel_hi:[1,0]
	v_exp_f32_e32 v142, v142
	v_exp_f32_e32 v143, v143
	v_rcp_f32_e32 v140, v140
	v_rcp_f32_e32 v141, v141
	s_mov_b64 s[8:9], 0
	v_pk_add_f32 v[142:143], v[142:143], 1.0 op_sel_hi:[1,0]
	v_pk_mul_f32 v[140:141], v[136:137], v[140:141]
	v_rcp_f32_e32 v142, v142
	v_rcp_f32_e32 v143, v143
	v_pk_mul_f32 v[136:137], v[146:147], v[138:139]
	v_cvt_pk_bf16_f32 v138, v140, v141
	v_add_u32_e32 v140, s4, v200
	v_pk_mul_f32 v[142:143], v[136:137], v[142:143]
	v_mad_i64_i32 v[140:141], s[4:5], v140, s19, v[148:149]
	v_cvt_pk_bf16_f32 v136, v152, v153
	v_cvt_pk_bf16_f32 v137, v154, v155
	v_cvt_pk_bf16_f32 v139, v142, v143
	v_lshl_add_u64 v[140:141], v[140:141], 0, v[150:151]
	s_mov_b64 s[4:5], 0
	global_store_dwordx4 v[140:141], v[136:139], off
	s_and_saveexec_b64 s[22:23], s[24:25]
	s_cbranch_execz .LBB0_1401
	v_readlane_b32 s8, v255, 10
	s_mov_b32 s42, s57
	v_add_u32_e32 v160, -14, v169
	s_ashr_i32 s57, s56, 31
	v_readlane_b32 s9, v255, 11
	v_lshl_add_u64 v[136:137], s[56:57], 1, v[160:161]
	s_movk_i32 s19, 0x2c00
	v_mov_b64_e32 v[138:139], s[8:9]
	v_mad_u64_u32 v[138:139], s[8:9], v136, s19, v[138:139]
	v_mad_i32_i24 v139, v137, s19, v139
	v_lshl_add_u64 v[136:137], v[174:175], 2, v[138:139]
	s_cmp_eq_u32 s18, 7
	s_mov_b64 s[24:25], 0
	global_store_dwordx4 v[136:137], v[128:131], off nt
	global_store_dwordx4 v[136:137], v[132:135], off offset:16
	s_cbranch_scc0 .LBB0_1400
	s_ashr_i32 s8, s56, 3
	s_ashr_i32 s9, s8, 31
	s_mov_b64 s[24:25], -1
